# nt hint on the phase 1 x row loads and the final norm output stores
# speedup vs baseline: 1.0020x; 1.0020x over previous
.Lp20_group:
	s_lshl_b32 s18, s10, 15
	s_add_u32 s18, s18, 0x18001000
	s_add_u32 s14, s4, s18
	s_addc_u32 s15, s5, 0
	s_lshl_b32 s18, s10, 16
	s_add_u32 s18, s18, 0x1000
	s_add_u32 s16, s6, s18
	s_addc_u32 s17, s7, 0
	global_load_dwordx4 v[0:3], v150, s[14:15] offset:-4096 nt
	global_load_dwordx4 v[4:7], v150, s[14:15] offset:-3072 nt
	global_load_dwordx4 v[8:11], v150, s[14:15] offset:-2048 nt
	global_load_dwordx4 v[12:15], v150, s[14:15] offset:-1024 nt
	global_load_dwordx4 v[16:19], v150, s[14:15] offset:0 nt
	global_load_dwordx4 v[20:23], v150, s[14:15] offset:1024 nt
	global_load_dwordx4 v[24:27], v150, s[14:15] offset:2048 nt
	global_load_dwordx4 v[28:31], v150, s[14:15] offset:3072 nt
	s_add_u32 s14, s14, 0x2000
	s_addc_u32 s15, s15, 0
	global_load_dwordx4 v[32:35], v150, s[14:15] offset:-4096 nt
	global_load_dwordx4 v[36:39], v150, s[14:15] offset:-3072 nt
	global_load_dwordx4 v[40:43], v150, s[14:15] offset:-2048 nt
	global_load_dwordx4 v[44:47], v150, s[14:15] offset:-1024 nt
	global_load_dwordx4 v[48:51], v150, s[14:15] offset:0 nt
	global_load_dwordx4 v[52:55], v150, s[14:15] offset:1024 nt
	global_load_dwordx4 v[56:59], v150, s[14:15] offset:2048 nt
	global_load_dwordx4 v[60:63], v150, s[14:15] offset:3072 nt
	s_add_u32 s14, s14, 0x2000
	s_addc_u32 s15, s15, 0
	global_load_dwordx4 v[64:67], v150, s[14:15] offset:-4096 nt
	global_load_dwordx4 v[68:71], v150, s[14:15] offset:-3072 nt
	global_load_dwordx4 v[72:75], v150, s[14:15] offset:-2048 nt
	global_load_dwordx4 v[76:79], v150, s[14:15] offset:-1024 nt
	global_load_dwordx4 v[80:83], v150, s[14:15] offset:0 nt
	global_load_dwordx4 v[84:87], v150, s[14:15] offset:1024 nt
	global_load_dwordx4 v[88:91], v150, s[14:15] offset:2048 nt
	global_load_dwordx4 v[92:95], v150, s[14:15] offset:3072 nt
	s_add_u32 s14, s14, 0x2000
	s_addc_u32 s15, s15, 0
	global_load_dwordx4 v[96:99], v150, s[14:15] offset:-4096 nt
	global_load_dwordx4 v[100:103], v150, s[14:15] offset:-3072 nt
	global_load_dwordx4 v[104:107], v150, s[14:15] offset:-2048 nt
	global_load_dwordx4 v[108:111], v150, s[14:15] offset:-1024 nt
	global_load_dwordx4 v[112:115], v150, s[14:15] offset:0 nt
	global_load_dwordx4 v[116:119], v150, s[14:15] offset:1024 nt
	global_load_dwordx4 v[120:123], v150, s[14:15] offset:2048 nt
	global_load_dwordx4 v[124:127], v150, s[14:15] offset:3072 nt
	s_waitcnt vmcnt(30)
	v_lshlrev_b32_e32 v164, 16, v0
	v_and_b32_e32 v165, 0xffff0000, v0
	v_lshlrev_b32_e32 v166, 16, v1
	v_and_b32_e32 v167, 0xffff0000, v1
	v_lshlrev_b32_e32 v168, 16, v2
	v_and_b32_e32 v169, 0xffff0000, v2
	v_lshlrev_b32_e32 v170, 16, v3
	v_and_b32_e32 v171, 0xffff0000, v3
	v_lshlrev_b32_e32 v172, 16, v4
	v_and_b32_e32 v173, 0xffff0000, v4
	v_lshlrev_b32_e32 v174, 16, v5
	v_and_b32_e32 v175, 0xffff0000, v5
	v_lshlrev_b32_e32 v176, 16, v6
	v_and_b32_e32 v177, 0xffff0000, v6
	v_lshlrev_b32_e32 v178, 16, v7
	v_and_b32_e32 v179, 0xffff0000, v7
	s_waitcnt vmcnt(28)
	v_lshlrev_b32_e32 v180, 16, v8
	v_and_b32_e32 v181, 0xffff0000, v8
	v_lshlrev_b32_e32 v182, 16, v9
	v_and_b32_e32 v183, 0xffff0000, v9
	v_lshlrev_b32_e32 v184, 16, v10
	v_and_b32_e32 v185, 0xffff0000, v10
	v_lshlrev_b32_e32 v186, 16, v11
	v_and_b32_e32 v187, 0xffff0000, v11
	v_lshlrev_b32_e32 v188, 16, v12
	v_and_b32_e32 v189, 0xffff0000, v12
	v_lshlrev_b32_e32 v190, 16, v13
	v_and_b32_e32 v191, 0xffff0000, v13
	v_lshlrev_b32_e32 v192, 16, v14
	v_and_b32_e32 v193, 0xffff0000, v14
	v_lshlrev_b32_e32 v194, 16, v15
	v_and_b32_e32 v195, 0xffff0000, v15
	v_pk_mul_f32 v[196:197], v[164:165], v[164:165]
	v_pk_mul_f32 v[198:199], v[180:181], v[180:181]
	v_pk_fma_f32 v[196:197], v[166:167], v[166:167], v[196:197]
	v_pk_fma_f32 v[198:199], v[182:183], v[182:183], v[198:199]
	v_pk_fma_f32 v[196:197], v[168:169], v[168:169], v[196:197]
	v_pk_fma_f32 v[198:199], v[184:185], v[184:185], v[198:199]
	v_pk_fma_f32 v[196:197], v[170:171], v[170:171], v[196:197]
	v_pk_fma_f32 v[198:199], v[186:187], v[186:187], v[198:199]
	v_pk_fma_f32 v[196:197], v[172:173], v[172:173], v[196:197]
	v_pk_fma_f32 v[198:199], v[188:189], v[188:189], v[198:199]
	v_pk_fma_f32 v[196:197], v[174:175], v[174:175], v[196:197]
	v_pk_fma_f32 v[198:199], v[190:191], v[190:191], v[198:199]
	v_pk_fma_f32 v[196:197], v[176:177], v[176:177], v[196:197]
	v_pk_fma_f32 v[198:199], v[192:193], v[192:193], v[198:199]
	v_pk_fma_f32 v[196:197], v[178:179], v[178:179], v[196:197]
	v_pk_fma_f32 v[198:199], v[194:195], v[194:195], v[198:199]
	v_add_f32_e32 v196, v196, v197
	v_add_f32_e32 v198, v198, v199
	ds_bpermute_b32 v200, v144, v196
	ds_bpermute_b32 v201, v144, v198
	s_waitcnt lgkmcnt(1)
	v_add_f32_e32 v196, v196, v200
	s_waitcnt lgkmcnt(0)
	v_add_f32_e32 v198, v198, v201
	ds_bpermute_b32 v200, v145, v196
	ds_bpermute_b32 v201, v145, v198
	s_waitcnt lgkmcnt(1)
	v_add_f32_e32 v196, v196, v200
	s_waitcnt lgkmcnt(0)
	v_add_f32_e32 v198, v198, v201
	ds_bpermute_b32 v200, v146, v196
	ds_bpermute_b32 v201, v146, v198
	s_waitcnt lgkmcnt(1)
	v_add_f32_e32 v196, v196, v200
	s_waitcnt lgkmcnt(0)
	v_add_f32_e32 v198, v198, v201
	ds_bpermute_b32 v200, v147, v196
	ds_bpermute_b32 v201, v147, v198
	s_waitcnt lgkmcnt(1)
	v_add_f32_e32 v196, v196, v200
	s_waitcnt lgkmcnt(0)
	v_add_f32_e32 v198, v198, v201
	ds_bpermute_b32 v200, v148, v196
	ds_bpermute_b32 v201, v148, v198
	s_waitcnt lgkmcnt(1)
	v_add_f32_e32 v196, v196, v200
	s_waitcnt lgkmcnt(0)
	v_add_f32_e32 v198, v198, v201
	ds_bpermute_b32 v200, v149, v196
	ds_bpermute_b32 v201, v149, v198
	s_waitcnt lgkmcnt(1)
	v_add_f32_e32 v196, v196, v200
	s_waitcnt lgkmcnt(0)
	v_add_f32_e32 v198, v198, v201
	v_mov_b32_e32 v200, 0x358637bd
	v_fmamk_f32 v196, v196, 0x3a800000, v200
	v_fmamk_f32 v198, v198, 0x3a800000, v200
	v_rsq_f32_e32 v202, v196
	v_rsq_f32_e32 v204, v198
	v_pk_mul_f32 v[164:165], v[164:165], v[202:203] op_sel_hi:[1,0]
	v_pk_mul_f32 v[166:167], v[166:167], v[202:203] op_sel_hi:[1,0]
	v_pk_mul_f32 v[168:169], v[168:169], v[202:203] op_sel_hi:[1,0]
	v_pk_mul_f32 v[170:171], v[170:171], v[202:203] op_sel_hi:[1,0]
	v_pk_mul_f32 v[172:173], v[172:173], v[202:203] op_sel_hi:[1,0]
	v_pk_mul_f32 v[174:175], v[174:175], v[202:203] op_sel_hi:[1,0]
	v_pk_mul_f32 v[176:177], v[176:177], v[202:203] op_sel_hi:[1,0]
	v_pk_mul_f32 v[178:179], v[178:179], v[202:203] op_sel_hi:[1,0]
	v_pk_mul_f32 v[164:165], v[128:129], v[164:165]
	v_pk_mul_f32 v[166:167], v[130:131], v[166:167]
	v_pk_mul_f32 v[168:169], v[132:133], v[168:169]
	v_pk_mul_f32 v[170:171], v[134:135], v[170:171]
	v_pk_mul_f32 v[172:173], v[136:137], v[172:173]
	v_pk_mul_f32 v[174:175], v[138:139], v[174:175]
	v_pk_mul_f32 v[176:177], v[140:141], v[176:177]
	v_pk_mul_f32 v[178:179], v[142:143], v[178:179]
	global_store_dwordx4 v151, v[164:167], s[16:17] offset:-4096 nt
	global_store_dwordx4 v151, v[168:171], s[16:17] offset:-4080 nt
	global_store_dwordx4 v151, v[172:175], s[16:17] offset:-2048 nt
	global_store_dwordx4 v151, v[176:179], s[16:17] offset:-2032 nt
	v_pk_mul_f32 v[180:181], v[180:181], v[204:205] op_sel_hi:[1,0]
	v_pk_mul_f32 v[182:183], v[182:183], v[204:205] op_sel_hi:[1,0]
	v_pk_mul_f32 v[184:185], v[184:185], v[204:205] op_sel_hi:[1,0]
	v_pk_mul_f32 v[186:187], v[186:187], v[204:205] op_sel_hi:[1,0]
	v_pk_mul_f32 v[188:189], v[188:189], v[204:205] op_sel_hi:[1,0]
	v_pk_mul_f32 v[190:191], v[190:191], v[204:205] op_sel_hi:[1,0]
	v_pk_mul_f32 v[192:193], v[192:193], v[204:205] op_sel_hi:[1,0]
	v_pk_mul_f32 v[194:195], v[194:195], v[204:205] op_sel_hi:[1,0]
	v_pk_mul_f32 v[180:181], v[128:129], v[180:181]
	v_pk_mul_f32 v[182:183], v[130:131], v[182:183]
	v_pk_mul_f32 v[184:185], v[132:133], v[184:185]
	v_pk_mul_f32 v[186:187], v[134:135], v[186:187]
	v_pk_mul_f32 v[188:189], v[136:137], v[188:189]
	v_pk_mul_f32 v[190:191], v[138:139], v[190:191]
	v_pk_mul_f32 v[192:193], v[140:141], v[192:193]
	v_pk_mul_f32 v[194:195], v[142:143], v[194:195]
	global_store_dwordx4 v151, v[180:183], s[16:17] offset:0 nt
	global_store_dwordx4 v151, v[184:187], s[16:17] offset:16 nt
	global_store_dwordx4 v151, v[188:191], s[16:17] offset:2048 nt
	global_store_dwordx4 v151, v[192:195], s[16:17] offset:2064 nt
	s_waitcnt vmcnt(34)
	v_lshlrev_b32_e32 v164, 16, v16
	v_and_b32_e32 v165, 0xffff0000, v16
	v_lshlrev_b32_e32 v166, 16, v17
	v_and_b32_e32 v167, 0xffff0000, v17
	v_lshlrev_b32_e32 v168, 16, v18
	v_and_b32_e32 v169, 0xffff0000, v18
	v_lshlrev_b32_e32 v170, 16, v19
	v_and_b32_e32 v171, 0xffff0000, v19
	v_lshlrev_b32_e32 v172, 16, v20
	v_and_b32_e32 v173, 0xffff0000, v20
	v_lshlrev_b32_e32 v174, 16, v21
	v_and_b32_e32 v175, 0xffff0000, v21
	v_lshlrev_b32_e32 v176, 16, v22
	v_and_b32_e32 v177, 0xffff0000, v22
	v_lshlrev_b32_e32 v178, 16, v23
	v_and_b32_e32 v179, 0xffff0000, v23
	s_waitcnt vmcnt(32)
	v_lshlrev_b32_e32 v180, 16, v24
	v_and_b32_e32 v181, 0xffff0000, v24
	v_lshlrev_b32_e32 v182, 16, v25
	v_and_b32_e32 v183, 0xffff0000, v25
	v_lshlrev_b32_e32 v184, 16, v26
	v_and_b32_e32 v185, 0xffff0000, v26
	v_lshlrev_b32_e32 v186, 16, v27
	v_and_b32_e32 v187, 0xffff0000, v27
	v_lshlrev_b32_e32 v188, 16, v28
	v_and_b32_e32 v189, 0xffff0000, v28
	v_lshlrev_b32_e32 v190, 16, v29
	v_and_b32_e32 v191, 0xffff0000, v29
	v_lshlrev_b32_e32 v192, 16, v30
	v_and_b32_e32 v193, 0xffff0000, v30
	v_lshlrev_b32_e32 v194, 16, v31
	v_and_b32_e32 v195, 0xffff0000, v31
	v_pk_mul_f32 v[196:197], v[164:165], v[164:165]
	v_pk_mul_f32 v[198:199], v[180:181], v[180:181]
	v_pk_fma_f32 v[196:197], v[166:167], v[166:167], v[196:197]
	v_pk_fma_f32 v[198:199], v[182:183], v[182:183], v[198:199]
	v_pk_fma_f32 v[196:197], v[168:169], v[168:169], v[196:197]
	v_pk_fma_f32 v[198:199], v[184:185], v[184:185], v[198:199]
	v_pk_fma_f32 v[196:197], v[170:171], v[170:171], v[196:197]
	v_pk_fma_f32 v[198:199], v[186:187], v[186:187], v[198:199]
	v_pk_fma_f32 v[196:197], v[172:173], v[172:173], v[196:197]
	v_pk_fma_f32 v[198:199], v[188:189], v[188:189], v[198:199]
	v_pk_fma_f32 v[196:197], v[174:175], v[174:175], v[196:197]
	v_pk_fma_f32 v[198:199], v[190:191], v[190:191], v[198:199]
	v_pk_fma_f32 v[196:197], v[176:177], v[176:177], v[196:197]
	v_pk_fma_f32 v[198:199], v[192:193], v[192:193], v[198:199]
	v_pk_fma_f32 v[196:197], v[178:179], v[178:179], v[196:197]
	v_pk_fma_f32 v[198:199], v[194:195], v[194:195], v[198:199]
	v_add_f32_e32 v196, v196, v197
	v_add_f32_e32 v198, v198, v199
	ds_bpermute_b32 v200, v144, v196
	ds_bpermute_b32 v201, v144, v198
	s_waitcnt lgkmcnt(1)
	v_add_f32_e32 v196, v196, v200
	s_waitcnt lgkmcnt(0)
	v_add_f32_e32 v198, v198, v201
	ds_bpermute_b32 v200, v145, v196
	ds_bpermute_b32 v201, v145, v198
	s_waitcnt lgkmcnt(1)
	v_add_f32_e32 v196, v196, v200
	s_waitcnt lgkmcnt(0)
	v_add_f32_e32 v198, v198, v201
	ds_bpermute_b32 v200, v146, v196
	ds_bpermute_b32 v201, v146, v198
	s_waitcnt lgkmcnt(1)
	v_add_f32_e32 v196, v196, v200
	s_waitcnt lgkmcnt(0)
	v_add_f32_e32 v198, v198, v201
	ds_bpermute_b32 v200, v147, v196
	ds_bpermute_b32 v201, v147, v198
	s_waitcnt lgkmcnt(1)
	v_add_f32_e32 v196, v196, v200
	s_waitcnt lgkmcnt(0)
	v_add_f32_e32 v198, v198, v201
	ds_bpermute_b32 v200, v148, v196
	ds_bpermute_b32 v201, v148, v198
	s_waitcnt lgkmcnt(1)
	v_add_f32_e32 v196, v196, v200
	s_waitcnt lgkmcnt(0)
	v_add_f32_e32 v198, v198, v201
	ds_bpermute_b32 v200, v149, v196
	ds_bpermute_b32 v201, v149, v198
	s_waitcnt lgkmcnt(1)
	v_add_f32_e32 v196, v196, v200
	s_waitcnt lgkmcnt(0)
	v_add_f32_e32 v198, v198, v201
	v_mov_b32_e32 v200, 0x358637bd
	v_fmamk_f32 v196, v196, 0x3a800000, v200
	v_fmamk_f32 v198, v198, 0x3a800000, v200
	v_rsq_f32_e32 v202, v196
	v_rsq_f32_e32 v204, v198
	s_add_u32 s16, s16, 0x2000
	s_addc_u32 s17, s17, 0
	v_pk_mul_f32 v[164:165], v[164:165], v[202:203] op_sel_hi:[1,0]
	v_pk_mul_f32 v[166:167], v[166:167], v[202:203] op_sel_hi:[1,0]
	v_pk_mul_f32 v[168:169], v[168:169], v[202:203] op_sel_hi:[1,0]
	v_pk_mul_f32 v[170:171], v[170:171], v[202:203] op_sel_hi:[1,0]
	v_pk_mul_f32 v[172:173], v[172:173], v[202:203] op_sel_hi:[1,0]
	v_pk_mul_f32 v[174:175], v[174:175], v[202:203] op_sel_hi:[1,0]
	v_pk_mul_f32 v[176:177], v[176:177], v[202:203] op_sel_hi:[1,0]
	v_pk_mul_f32 v[178:179], v[178:179], v[202:203] op_sel_hi:[1,0]
	v_pk_mul_f32 v[164:165], v[128:129], v[164:165]
	v_pk_mul_f32 v[166:167], v[130:131], v[166:167]
	v_pk_mul_f32 v[168:169], v[132:133], v[168:169]
	v_pk_mul_f32 v[170:171], v[134:135], v[170:171]
	v_pk_mul_f32 v[172:173], v[136:137], v[172:173]
	v_pk_mul_f32 v[174:175], v[138:139], v[174:175]
	v_pk_mul_f32 v[176:177], v[140:141], v[176:177]
	v_pk_mul_f32 v[178:179], v[142:143], v[178:179]
	global_store_dwordx4 v151, v[164:167], s[16:17] offset:-4096 nt
	global_store_dwordx4 v151, v[168:171], s[16:17] offset:-4080 nt
	global_store_dwordx4 v151, v[172:175], s[16:17] offset:-2048 nt
	global_store_dwordx4 v151, v[176:179], s[16:17] offset:-2032 nt
	v_pk_mul_f32 v[180:181], v[180:181], v[204:205] op_sel_hi:[1,0]
	v_pk_mul_f32 v[182:183], v[182:183], v[204:205] op_sel_hi:[1,0]
	v_pk_mul_f32 v[184:185], v[184:185], v[204:205] op_sel_hi:[1,0]
	v_pk_mul_f32 v[186:187], v[186:187], v[204:205] op_sel_hi:[1,0]
	v_pk_mul_f32 v[188:189], v[188:189], v[204:205] op_sel_hi:[1,0]
	v_pk_mul_f32 v[190:191], v[190:191], v[204:205] op_sel_hi:[1,0]
	v_pk_mul_f32 v[192:193], v[192:193], v[204:205] op_sel_hi:[1,0]
	v_pk_mul_f32 v[194:195], v[194:195], v[204:205] op_sel_hi:[1,0]
	v_pk_mul_f32 v[180:181], v[128:129], v[180:181]
	v_pk_mul_f32 v[182:183], v[130:131], v[182:183]
	v_pk_mul_f32 v[184:185], v[132:133], v[184:185]
	v_pk_mul_f32 v[186:187], v[134:135], v[186:187]
	v_pk_mul_f32 v[188:189], v[136:137], v[188:189]
	v_pk_mul_f32 v[190:191], v[138:139], v[190:191]
	v_pk_mul_f32 v[192:193], v[140:141], v[192:193]
	v_pk_mul_f32 v[194:195], v[142:143], v[194:195]
	global_store_dwordx4 v151, v[180:183], s[16:17] offset:0 nt
	global_store_dwordx4 v151, v[184:187], s[16:17] offset:16 nt
	global_store_dwordx4 v151, v[188:191], s[16:17] offset:2048 nt
	global_store_dwordx4 v151, v[192:195], s[16:17] offset:2064 nt
	s_waitcnt vmcnt(38)
	v_lshlrev_b32_e32 v164, 16, v32
	v_and_b32_e32 v165, 0xffff0000, v32
	v_lshlrev_b32_e32 v166, 16, v33
	v_and_b32_e32 v167, 0xffff0000, v33
	v_lshlrev_b32_e32 v168, 16, v34
	v_and_b32_e32 v169, 0xffff0000, v34
	v_lshlrev_b32_e32 v170, 16, v35
	v_and_b32_e32 v171, 0xffff0000, v35
	v_lshlrev_b32_e32 v172, 16, v36
	v_and_b32_e32 v173, 0xffff0000, v36
	v_lshlrev_b32_e32 v174, 16, v37
	v_and_b32_e32 v175, 0xffff0000, v37
	v_lshlrev_b32_e32 v176, 16, v38
	v_and_b32_e32 v177, 0xffff0000, v38
	v_lshlrev_b32_e32 v178, 16, v39
	v_and_b32_e32 v179, 0xffff0000, v39
	s_waitcnt vmcnt(36)
	v_lshlrev_b32_e32 v180, 16, v40
	v_and_b32_e32 v181, 0xffff0000, v40
	v_lshlrev_b32_e32 v182, 16, v41
	v_and_b32_e32 v183, 0xffff0000, v41
	v_lshlrev_b32_e32 v184, 16, v42
	v_and_b32_e32 v185, 0xffff0000, v42
	v_lshlrev_b32_e32 v186, 16, v43
	v_and_b32_e32 v187, 0xffff0000, v43
	v_lshlrev_b32_e32 v188, 16, v44
	v_and_b32_e32 v189, 0xffff0000, v44
	v_lshlrev_b32_e32 v190, 16, v45
	v_and_b32_e32 v191, 0xffff0000, v45
	v_lshlrev_b32_e32 v192, 16, v46
	v_and_b32_e32 v193, 0xffff0000, v46
	v_lshlrev_b32_e32 v194, 16, v47
	v_and_b32_e32 v195, 0xffff0000, v47
	v_pk_mul_f32 v[196:197], v[164:165], v[164:165]
	v_pk_mul_f32 v[198:199], v[180:181], v[180:181]
	v_pk_fma_f32 v[196:197], v[166:167], v[166:167], v[196:197]
	v_pk_fma_f32 v[198:199], v[182:183], v[182:183], v[198:199]
	v_pk_fma_f32 v[196:197], v[168:169], v[168:169], v[196:197]
	v_pk_fma_f32 v[198:199], v[184:185], v[184:185], v[198:199]
	v_pk_fma_f32 v[196:197], v[170:171], v[170:171], v[196:197]
	v_pk_fma_f32 v[198:199], v[186:187], v[186:187], v[198:199]
	v_pk_fma_f32 v[196:197], v[172:173], v[172:173], v[196:197]
	v_pk_fma_f32 v[198:199], v[188:189], v[188:189], v[198:199]
	v_pk_fma_f32 v[196:197], v[174:175], v[174:175], v[196:197]
	v_pk_fma_f32 v[198:199], v[190:191], v[190:191], v[198:199]
	v_pk_fma_f32 v[196:197], v[176:177], v[176:177], v[196:197]
	v_pk_fma_f32 v[198:199], v[192:193], v[192:193], v[198:199]
	v_pk_fma_f32 v[196:197], v[178:179], v[178:179], v[196:197]
	v_pk_fma_f32 v[198:199], v[194:195], v[194:195], v[198:199]
	v_add_f32_e32 v196, v196, v197
	v_add_f32_e32 v198, v198, v199
	ds_bpermute_b32 v200, v144, v196
	ds_bpermute_b32 v201, v144, v198
	s_waitcnt lgkmcnt(1)
	v_add_f32_e32 v196, v196, v200
	s_waitcnt lgkmcnt(0)
	v_add_f32_e32 v198, v198, v201
	ds_bpermute_b32 v200, v145, v196
	ds_bpermute_b32 v201, v145, v198
	s_waitcnt lgkmcnt(1)
	v_add_f32_e32 v196, v196, v200
	s_waitcnt lgkmcnt(0)
	v_add_f32_e32 v198, v198, v201
	ds_bpermute_b32 v200, v146, v196
	ds_bpermute_b32 v201, v146, v198
	s_waitcnt lgkmcnt(1)
	v_add_f32_e32 v196, v196, v200
	s_waitcnt lgkmcnt(0)
	v_add_f32_e32 v198, v198, v201
	ds_bpermute_b32 v200, v147, v196
	ds_bpermute_b32 v201, v147, v198
	s_waitcnt lgkmcnt(1)
	v_add_f32_e32 v196, v196, v200
	s_waitcnt lgkmcnt(0)
	v_add_f32_e32 v198, v198, v201
	ds_bpermute_b32 v200, v148, v196
	ds_bpermute_b32 v201, v148, v198
	s_waitcnt lgkmcnt(1)
	v_add_f32_e32 v196, v196, v200
	s_waitcnt lgkmcnt(0)
	v_add_f32_e32 v198, v198, v201
	ds_bpermute_b32 v200, v149, v196
	ds_bpermute_b32 v201, v149, v198
	s_waitcnt lgkmcnt(1)
	v_add_f32_e32 v196, v196, v200
	s_waitcnt lgkmcnt(0)
	v_add_f32_e32 v198, v198, v201
	v_mov_b32_e32 v200, 0x358637bd
	v_fmamk_f32 v196, v196, 0x3a800000, v200
	v_fmamk_f32 v198, v198, 0x3a800000, v200
	v_rsq_f32_e32 v202, v196
	v_rsq_f32_e32 v204, v198
	s_add_u32 s16, s16, 0x2000
	s_addc_u32 s17, s17, 0
	v_pk_mul_f32 v[164:165], v[164:165], v[202:203] op_sel_hi:[1,0]
	v_pk_mul_f32 v[166:167], v[166:167], v[202:203] op_sel_hi:[1,0]
	v_pk_mul_f32 v[168:169], v[168:169], v[202:203] op_sel_hi:[1,0]
	v_pk_mul_f32 v[170:171], v[170:171], v[202:203] op_sel_hi:[1,0]
	v_pk_mul_f32 v[172:173], v[172:173], v[202:203] op_sel_hi:[1,0]
	v_pk_mul_f32 v[174:175], v[174:175], v[202:203] op_sel_hi:[1,0]
	v_pk_mul_f32 v[176:177], v[176:177], v[202:203] op_sel_hi:[1,0]
	v_pk_mul_f32 v[178:179], v[178:179], v[202:203] op_sel_hi:[1,0]
	v_pk_mul_f32 v[164:165], v[128:129], v[164:165]
	v_pk_mul_f32 v[166:167], v[130:131], v[166:167]
	v_pk_mul_f32 v[168:169], v[132:133], v[168:169]
	v_pk_mul_f32 v[170:171], v[134:135], v[170:171]
	v_pk_mul_f32 v[172:173], v[136:137], v[172:173]
	v_pk_mul_f32 v[174:175], v[138:139], v[174:175]
	v_pk_mul_f32 v[176:177], v[140:141], v[176:177]
	v_pk_mul_f32 v[178:179], v[142:143], v[178:179]
	global_store_dwordx4 v151, v[164:167], s[16:17] offset:-4096 nt
	global_store_dwordx4 v151, v[168:171], s[16:17] offset:-4080 nt
	global_store_dwordx4 v151, v[172:175], s[16:17] offset:-2048 nt
	global_store_dwordx4 v151, v[176:179], s[16:17] offset:-2032 nt
	v_pk_mul_f32 v[180:181], v[180:181], v[204:205] op_sel_hi:[1,0]
	v_pk_mul_f32 v[182:183], v[182:183], v[204:205] op_sel_hi:[1,0]
	v_pk_mul_f32 v[184:185], v[184:185], v[204:205] op_sel_hi:[1,0]
	v_pk_mul_f32 v[186:187], v[186:187], v[204:205] op_sel_hi:[1,0]
	v_pk_mul_f32 v[188:189], v[188:189], v[204:205] op_sel_hi:[1,0]
	v_pk_mul_f32 v[190:191], v[190:191], v[204:205] op_sel_hi:[1,0]
	v_pk_mul_f32 v[192:193], v[192:193], v[204:205] op_sel_hi:[1,0]
	v_pk_mul_f32 v[194:195], v[194:195], v[204:205] op_sel_hi:[1,0]
	v_pk_mul_f32 v[180:181], v[128:129], v[180:181]
	v_pk_mul_f32 v[182:183], v[130:131], v[182:183]
	v_pk_mul_f32 v[184:185], v[132:133], v[184:185]
	v_pk_mul_f32 v[186:187], v[134:135], v[186:187]
	v_pk_mul_f32 v[188:189], v[136:137], v[188:189]
	v_pk_mul_f32 v[190:191], v[138:139], v[190:191]
	v_pk_mul_f32 v[192:193], v[140:141], v[192:193]
	v_pk_mul_f32 v[194:195], v[142:143], v[194:195]
	global_store_dwordx4 v151, v[180:183], s[16:17] offset:0 nt
	global_store_dwordx4 v151, v[184:187], s[16:17] offset:16 nt
	global_store_dwordx4 v151, v[188:191], s[16:17] offset:2048 nt
	global_store_dwordx4 v151, v[192:195], s[16:17] offset:2064 nt
	s_waitcnt vmcnt(42)
	v_lshlrev_b32_e32 v164, 16, v48
	v_and_b32_e32 v165, 0xffff0000, v48
	v_lshlrev_b32_e32 v166, 16, v49
	v_and_b32_e32 v167, 0xffff0000, v49
	v_lshlrev_b32_e32 v168, 16, v50
	v_and_b32_e32 v169, 0xffff0000, v50
	v_lshlrev_b32_e32 v170, 16, v51
	v_and_b32_e32 v171, 0xffff0000, v51
	v_lshlrev_b32_e32 v172, 16, v52
	v_and_b32_e32 v173, 0xffff0000, v52
	v_lshlrev_b32_e32 v174, 16, v53
	v_and_b32_e32 v175, 0xffff0000, v53
	v_lshlrev_b32_e32 v176, 16, v54
	v_and_b32_e32 v177, 0xffff0000, v54
	v_lshlrev_b32_e32 v178, 16, v55
	v_and_b32_e32 v179, 0xffff0000, v55
	s_waitcnt vmcnt(40)
	v_lshlrev_b32_e32 v180, 16, v56
	v_and_b32_e32 v181, 0xffff0000, v56
	v_lshlrev_b32_e32 v182, 16, v57
	v_and_b32_e32 v183, 0xffff0000, v57
	v_lshlrev_b32_e32 v184, 16, v58
	v_and_b32_e32 v185, 0xffff0000, v58
	v_lshlrev_b32_e32 v186, 16, v59
	v_and_b32_e32 v187, 0xffff0000, v59
	v_lshlrev_b32_e32 v188, 16, v60
	v_and_b32_e32 v189, 0xffff0000, v60
	v_lshlrev_b32_e32 v190, 16, v61
	v_and_b32_e32 v191, 0xffff0000, v61
	v_lshlrev_b32_e32 v192, 16, v62
	v_and_b32_e32 v193, 0xffff0000, v62
	v_lshlrev_b32_e32 v194, 16, v63
	v_and_b32_e32 v195, 0xffff0000, v63
	v_pk_mul_f32 v[196:197], v[164:165], v[164:165]
	v_pk_mul_f32 v[198:199], v[180:181], v[180:181]
	v_pk_fma_f32 v[196:197], v[166:167], v[166:167], v[196:197]
	v_pk_fma_f32 v[198:199], v[182:183], v[182:183], v[198:199]
	v_pk_fma_f32 v[196:197], v[168:169], v[168:169], v[196:197]
	v_pk_fma_f32 v[198:199], v[184:185], v[184:185], v[198:199]
	v_pk_fma_f32 v[196:197], v[170:171], v[170:171], v[196:197]
	v_pk_fma_f32 v[198:199], v[186:187], v[186:187], v[198:199]
	v_pk_fma_f32 v[196:197], v[172:173], v[172:173], v[196:197]
	v_pk_fma_f32 v[198:199], v[188:189], v[188:189], v[198:199]
	v_pk_fma_f32 v[196:197], v[174:175], v[174:175], v[196:197]
	v_pk_fma_f32 v[198:199], v[190:191], v[190:191], v[198:199]
	v_pk_fma_f32 v[196:197], v[176:177], v[176:177], v[196:197]
	v_pk_fma_f32 v[198:199], v[192:193], v[192:193], v[198:199]
	v_pk_fma_f32 v[196:197], v[178:179], v[178:179], v[196:197]
	v_pk_fma_f32 v[198:199], v[194:195], v[194:195], v[198:199]
	v_add_f32_e32 v196, v196, v197
	v_add_f32_e32 v198, v198, v199
	ds_bpermute_b32 v200, v144, v196
	ds_bpermute_b32 v201, v144, v198
	s_waitcnt lgkmcnt(1)
	v_add_f32_e32 v196, v196, v200
	s_waitcnt lgkmcnt(0)
	v_add_f32_e32 v198, v198, v201
	ds_bpermute_b32 v200, v145, v196
	ds_bpermute_b32 v201, v145, v198
	s_waitcnt lgkmcnt(1)
	v_add_f32_e32 v196, v196, v200
	s_waitcnt lgkmcnt(0)
	v_add_f32_e32 v198, v198, v201
	ds_bpermute_b32 v200, v146, v196
	ds_bpermute_b32 v201, v146, v198
	s_waitcnt lgkmcnt(1)
	v_add_f32_e32 v196, v196, v200
	s_waitcnt lgkmcnt(0)
	v_add_f32_e32 v198, v198, v201
	ds_bpermute_b32 v200, v147, v196
	ds_bpermute_b32 v201, v147, v198
	s_waitcnt lgkmcnt(1)
	v_add_f32_e32 v196, v196, v200
	s_waitcnt lgkmcnt(0)
	v_add_f32_e32 v198, v198, v201
	ds_bpermute_b32 v200, v148, v196
	ds_bpermute_b32 v201, v148, v198
	s_waitcnt lgkmcnt(1)
	v_add_f32_e32 v196, v196, v200
	s_waitcnt lgkmcnt(0)
	v_add_f32_e32 v198, v198, v201
	ds_bpermute_b32 v200, v149, v196
	ds_bpermute_b32 v201, v149, v198
	s_waitcnt lgkmcnt(1)
	v_add_f32_e32 v196, v196, v200
	s_waitcnt lgkmcnt(0)
	v_add_f32_e32 v198, v198, v201
	v_mov_b32_e32 v200, 0x358637bd
	v_fmamk_f32 v196, v196, 0x3a800000, v200
	v_fmamk_f32 v198, v198, 0x3a800000, v200
	v_rsq_f32_e32 v202, v196
	v_rsq_f32_e32 v204, v198
	s_add_u32 s16, s16, 0x2000
	s_addc_u32 s17, s17, 0
	v_pk_mul_f32 v[164:165], v[164:165], v[202:203] op_sel_hi:[1,0]
	v_pk_mul_f32 v[166:167], v[166:167], v[202:203] op_sel_hi:[1,0]
	v_pk_mul_f32 v[168:169], v[168:169], v[202:203] op_sel_hi:[1,0]
	v_pk_mul_f32 v[170:171], v[170:171], v[202:203] op_sel_hi:[1,0]
	v_pk_mul_f32 v[172:173], v[172:173], v[202:203] op_sel_hi:[1,0]
	v_pk_mul_f32 v[174:175], v[174:175], v[202:203] op_sel_hi:[1,0]
	v_pk_mul_f32 v[176:177], v[176:177], v[202:203] op_sel_hi:[1,0]
	v_pk_mul_f32 v[178:179], v[178:179], v[202:203] op_sel_hi:[1,0]
	v_pk_mul_f32 v[164:165], v[128:129], v[164:165]
	v_pk_mul_f32 v[166:167], v[130:131], v[166:167]
	v_pk_mul_f32 v[168:169], v[132:133], v[168:169]
	v_pk_mul_f32 v[170:171], v[134:135], v[170:171]
	v_pk_mul_f32 v[172:173], v[136:137], v[172:173]
	v_pk_mul_f32 v[174:175], v[138:139], v[174:175]
	v_pk_mul_f32 v[176:177], v[140:141], v[176:177]
	v_pk_mul_f32 v[178:179], v[142:143], v[178:179]
	global_store_dwordx4 v151, v[164:167], s[16:17] offset:-4096 nt
	global_store_dwordx4 v151, v[168:171], s[16:17] offset:-4080 nt
	global_store_dwordx4 v151, v[172:175], s[16:17] offset:-2048 nt
	global_store_dwordx4 v151, v[176:179], s[16:17] offset:-2032 nt
	v_pk_mul_f32 v[180:181], v[180:181], v[204:205] op_sel_hi:[1,0]
	v_pk_mul_f32 v[182:183], v[182:183], v[204:205] op_sel_hi:[1,0]
	v_pk_mul_f32 v[184:185], v[184:185], v[204:205] op_sel_hi:[1,0]
	v_pk_mul_f32 v[186:187], v[186:187], v[204:205] op_sel_hi:[1,0]
	v_pk_mul_f32 v[188:189], v[188:189], v[204:205] op_sel_hi:[1,0]
	v_pk_mul_f32 v[190:191], v[190:191], v[204:205] op_sel_hi:[1,0]
	v_pk_mul_f32 v[192:193], v[192:193], v[204:205] op_sel_hi:[1,0]
	v_pk_mul_f32 v[194:195], v[194:195], v[204:205] op_sel_hi:[1,0]
	v_pk_mul_f32 v[180:181], v[128:129], v[180:181]
	v_pk_mul_f32 v[182:183], v[130:131], v[182:183]
	v_pk_mul_f32 v[184:185], v[132:133], v[184:185]
	v_pk_mul_f32 v[186:187], v[134:135], v[186:187]
	v_pk_mul_f32 v[188:189], v[136:137], v[188:189]
	v_pk_mul_f32 v[190:191], v[138:139], v[190:191]
	v_pk_mul_f32 v[192:193], v[140:141], v[192:193]
	v_pk_mul_f32 v[194:195], v[142:143], v[194:195]
	global_store_dwordx4 v151, v[180:183], s[16:17] offset:0 nt
	global_store_dwordx4 v151, v[184:187], s[16:17] offset:16 nt
	global_store_dwordx4 v151, v[188:191], s[16:17] offset:2048 nt
	global_store_dwordx4 v151, v[192:195], s[16:17] offset:2064 nt
	s_waitcnt vmcnt(46)
	v_lshlrev_b32_e32 v164, 16, v64
	v_and_b32_e32 v165, 0xffff0000, v64
	v_lshlrev_b32_e32 v166, 16, v65
	v_and_b32_e32 v167, 0xffff0000, v65
	v_lshlrev_b32_e32 v168, 16, v66
	v_and_b32_e32 v169, 0xffff0000, v66
	v_lshlrev_b32_e32 v170, 16, v67
	v_and_b32_e32 v171, 0xffff0000, v67
	v_lshlrev_b32_e32 v172, 16, v68
	v_and_b32_e32 v173, 0xffff0000, v68
	v_lshlrev_b32_e32 v174, 16, v69
	v_and_b32_e32 v175, 0xffff0000, v69
	v_lshlrev_b32_e32 v176, 16, v70
	v_and_b32_e32 v177, 0xffff0000, v70
	v_lshlrev_b32_e32 v178, 16, v71
	v_and_b32_e32 v179, 0xffff0000, v71
	s_waitcnt vmcnt(44)
	v_lshlrev_b32_e32 v180, 16, v72
	v_and_b32_e32 v181, 0xffff0000, v72
	v_lshlrev_b32_e32 v182, 16, v73
	v_and_b32_e32 v183, 0xffff0000, v73
	v_lshlrev_b32_e32 v184, 16, v74
	v_and_b32_e32 v185, 0xffff0000, v74
	v_lshlrev_b32_e32 v186, 16, v75
	v_and_b32_e32 v187, 0xffff0000, v75
	v_lshlrev_b32_e32 v188, 16, v76
	v_and_b32_e32 v189, 0xffff0000, v76
	v_lshlrev_b32_e32 v190, 16, v77
	v_and_b32_e32 v191, 0xffff0000, v77
	v_lshlrev_b32_e32 v192, 16, v78
	v_and_b32_e32 v193, 0xffff0000, v78
	v_lshlrev_b32_e32 v194, 16, v79
	v_and_b32_e32 v195, 0xffff0000, v79
	v_pk_mul_f32 v[196:197], v[164:165], v[164:165]
	v_pk_mul_f32 v[198:199], v[180:181], v[180:181]
	v_pk_fma_f32 v[196:197], v[166:167], v[166:167], v[196:197]
	v_pk_fma_f32 v[198:199], v[182:183], v[182:183], v[198:199]
	v_pk_fma_f32 v[196:197], v[168:169], v[168:169], v[196:197]
	v_pk_fma_f32 v[198:199], v[184:185], v[184:185], v[198:199]
	v_pk_fma_f32 v[196:197], v[170:171], v[170:171], v[196:197]
	v_pk_fma_f32 v[198:199], v[186:187], v[186:187], v[198:199]
	v_pk_fma_f32 v[196:197], v[172:173], v[172:173], v[196:197]
	v_pk_fma_f32 v[198:199], v[188:189], v[188:189], v[198:199]
	v_pk_fma_f32 v[196:197], v[174:175], v[174:175], v[196:197]
	v_pk_fma_f32 v[198:199], v[190:191], v[190:191], v[198:199]
	v_pk_fma_f32 v[196:197], v[176:177], v[176:177], v[196:197]
	v_pk_fma_f32 v[198:199], v[192:193], v[192:193], v[198:199]
	v_pk_fma_f32 v[196:197], v[178:179], v[178:179], v[196:197]
	v_pk_fma_f32 v[198:199], v[194:195], v[194:195], v[198:199]
	v_add_f32_e32 v196, v196, v197
	v_add_f32_e32 v198, v198, v199
	ds_bpermute_b32 v200, v144, v196
	ds_bpermute_b32 v201, v144, v198
	s_waitcnt lgkmcnt(1)
	v_add_f32_e32 v196, v196, v200
	s_waitcnt lgkmcnt(0)
	v_add_f32_e32 v198, v198, v201
	ds_bpermute_b32 v200, v145, v196
	ds_bpermute_b32 v201, v145, v198
	s_waitcnt lgkmcnt(1)
	v_add_f32_e32 v196, v196, v200
	s_waitcnt lgkmcnt(0)
	v_add_f32_e32 v198, v198, v201
	ds_bpermute_b32 v200, v146, v196
	ds_bpermute_b32 v201, v146, v198
	s_waitcnt lgkmcnt(1)
	v_add_f32_e32 v196, v196, v200
	s_waitcnt lgkmcnt(0)
	v_add_f32_e32 v198, v198, v201
	ds_bpermute_b32 v200, v147, v196
	ds_bpermute_b32 v201, v147, v198
	s_waitcnt lgkmcnt(1)
	v_add_f32_e32 v196, v196, v200
	s_waitcnt lgkmcnt(0)
	v_add_f32_e32 v198, v198, v201
	ds_bpermute_b32 v200, v148, v196
	ds_bpermute_b32 v201, v148, v198
	s_waitcnt lgkmcnt(1)
	v_add_f32_e32 v196, v196, v200
	s_waitcnt lgkmcnt(0)
	v_add_f32_e32 v198, v198, v201
	ds_bpermute_b32 v200, v149, v196
	ds_bpermute_b32 v201, v149, v198
	s_waitcnt lgkmcnt(1)
	v_add_f32_e32 v196, v196, v200
	s_waitcnt lgkmcnt(0)
	v_add_f32_e32 v198, v198, v201
	v_mov_b32_e32 v200, 0x358637bd
	v_fmamk_f32 v196, v196, 0x3a800000, v200
	v_fmamk_f32 v198, v198, 0x3a800000, v200
	v_rsq_f32_e32 v202, v196
	v_rsq_f32_e32 v204, v198
	s_add_u32 s16, s16, 0x2000
	s_addc_u32 s17, s17, 0
	v_pk_mul_f32 v[164:165], v[164:165], v[202:203] op_sel_hi:[1,0]
	v_pk_mul_f32 v[166:167], v[166:167], v[202:203] op_sel_hi:[1,0]
	v_pk_mul_f32 v[168:169], v[168:169], v[202:203] op_sel_hi:[1,0]
	v_pk_mul_f32 v[170:171], v[170:171], v[202:203] op_sel_hi:[1,0]
	v_pk_mul_f32 v[172:173], v[172:173], v[202:203] op_sel_hi:[1,0]
	v_pk_mul_f32 v[174:175], v[174:175], v[202:203] op_sel_hi:[1,0]
	v_pk_mul_f32 v[176:177], v[176:177], v[202:203] op_sel_hi:[1,0]
	v_pk_mul_f32 v[178:179], v[178:179], v[202:203] op_sel_hi:[1,0]
	v_pk_mul_f32 v[164:165], v[128:129], v[164:165]
	v_pk_mul_f32 v[166:167], v[130:131], v[166:167]
	v_pk_mul_f32 v[168:169], v[132:133], v[168:169]
	v_pk_mul_f32 v[170:171], v[134:135], v[170:171]
	v_pk_mul_f32 v[172:173], v[136:137], v[172:173]
	v_pk_mul_f32 v[174:175], v[138:139], v[174:175]
	v_pk_mul_f32 v[176:177], v[140:141], v[176:177]
	v_pk_mul_f32 v[178:179], v[142:143], v[178:179]
	global_store_dwordx4 v151, v[164:167], s[16:17] offset:-4096 nt
	global_store_dwordx4 v151, v[168:171], s[16:17] offset:-4080 nt
	global_store_dwordx4 v151, v[172:175], s[16:17] offset:-2048 nt
	global_store_dwordx4 v151, v[176:179], s[16:17] offset:-2032 nt
	v_pk_mul_f32 v[180:181], v[180:181], v[204:205] op_sel_hi:[1,0]
	v_pk_mul_f32 v[182:183], v[182:183], v[204:205] op_sel_hi:[1,0]
	v_pk_mul_f32 v[184:185], v[184:185], v[204:205] op_sel_hi:[1,0]
	v_pk_mul_f32 v[186:187], v[186:187], v[204:205] op_sel_hi:[1,0]
	v_pk_mul_f32 v[188:189], v[188:189], v[204:205] op_sel_hi:[1,0]
	v_pk_mul_f32 v[190:191], v[190:191], v[204:205] op_sel_hi:[1,0]
	v_pk_mul_f32 v[192:193], v[192:193], v[204:205] op_sel_hi:[1,0]
	v_pk_mul_f32 v[194:195], v[194:195], v[204:205] op_sel_hi:[1,0]
	v_pk_mul_f32 v[180:181], v[128:129], v[180:181]
	v_pk_mul_f32 v[182:183], v[130:131], v[182:183]
	v_pk_mul_f32 v[184:185], v[132:133], v[184:185]
	v_pk_mul_f32 v[186:187], v[134:135], v[186:187]
	v_pk_mul_f32 v[188:189], v[136:137], v[188:189]
	v_pk_mul_f32 v[190:191], v[138:139], v[190:191]
	v_pk_mul_f32 v[192:193], v[140:141], v[192:193]
	v_pk_mul_f32 v[194:195], v[142:143], v[194:195]
	global_store_dwordx4 v151, v[180:183], s[16:17] offset:0 nt
	global_store_dwordx4 v151, v[184:187], s[16:17] offset:16 nt
	global_store_dwordx4 v151, v[188:191], s[16:17] offset:2048 nt
	global_store_dwordx4 v151, v[192:195], s[16:17] offset:2064 nt
	s_waitcnt vmcnt(50)
	v_lshlrev_b32_e32 v164, 16, v80
	v_and_b32_e32 v165, 0xffff0000, v80
	v_lshlrev_b32_e32 v166, 16, v81
	v_and_b32_e32 v167, 0xffff0000, v81
	v_lshlrev_b32_e32 v168, 16, v82
	v_and_b32_e32 v169, 0xffff0000, v82
	v_lshlrev_b32_e32 v170, 16, v83
	v_and_b32_e32 v171, 0xffff0000, v83
	v_lshlrev_b32_e32 v172, 16, v84
	v_and_b32_e32 v173, 0xffff0000, v84
	v_lshlrev_b32_e32 v174, 16, v85
	v_and_b32_e32 v175, 0xffff0000, v85
	v_lshlrev_b32_e32 v176, 16, v86
	v_and_b32_e32 v177, 0xffff0000, v86
	v_lshlrev_b32_e32 v178, 16, v87
	v_and_b32_e32 v179, 0xffff0000, v87
	s_waitcnt vmcnt(48)
	v_lshlrev_b32_e32 v180, 16, v88
	v_and_b32_e32 v181, 0xffff0000, v88
	v_lshlrev_b32_e32 v182, 16, v89
	v_and_b32_e32 v183, 0xffff0000, v89
	v_lshlrev_b32_e32 v184, 16, v90
	v_and_b32_e32 v185, 0xffff0000, v90
	v_lshlrev_b32_e32 v186, 16, v91
	v_and_b32_e32 v187, 0xffff0000, v91
	v_lshlrev_b32_e32 v188, 16, v92
	v_and_b32_e32 v189, 0xffff0000, v92
	v_lshlrev_b32_e32 v190, 16, v93
	v_and_b32_e32 v191, 0xffff0000, v93
	v_lshlrev_b32_e32 v192, 16, v94
	v_and_b32_e32 v193, 0xffff0000, v94
	v_lshlrev_b32_e32 v194, 16, v95
	v_and_b32_e32 v195, 0xffff0000, v95
	v_pk_mul_f32 v[196:197], v[164:165], v[164:165]
	v_pk_mul_f32 v[198:199], v[180:181], v[180:181]
	v_pk_fma_f32 v[196:197], v[166:167], v[166:167], v[196:197]
	v_pk_fma_f32 v[198:199], v[182:183], v[182:183], v[198:199]
	v_pk_fma_f32 v[196:197], v[168:169], v[168:169], v[196:197]
	v_pk_fma_f32 v[198:199], v[184:185], v[184:185], v[198:199]
	v_pk_fma_f32 v[196:197], v[170:171], v[170:171], v[196:197]
	v_pk_fma_f32 v[198:199], v[186:187], v[186:187], v[198:199]
	v_pk_fma_f32 v[196:197], v[172:173], v[172:173], v[196:197]
	v_pk_fma_f32 v[198:199], v[188:189], v[188:189], v[198:199]
	v_pk_fma_f32 v[196:197], v[174:175], v[174:175], v[196:197]
	v_pk_fma_f32 v[198:199], v[190:191], v[190:191], v[198:199]
	v_pk_fma_f32 v[196:197], v[176:177], v[176:177], v[196:197]
	v_pk_fma_f32 v[198:199], v[192:193], v[192:193], v[198:199]
	v_pk_fma_f32 v[196:197], v[178:179], v[178:179], v[196:197]
	v_pk_fma_f32 v[198:199], v[194:195], v[194:195], v[198:199]
	v_add_f32_e32 v196, v196, v197
	v_add_f32_e32 v198, v198, v199
	ds_bpermute_b32 v200, v144, v196
	ds_bpermute_b32 v201, v144, v198
	s_waitcnt lgkmcnt(1)
	v_add_f32_e32 v196, v196, v200
	s_waitcnt lgkmcnt(0)
	v_add_f32_e32 v198, v198, v201
	ds_bpermute_b32 v200, v145, v196
	ds_bpermute_b32 v201, v145, v198
	s_waitcnt lgkmcnt(1)
	v_add_f32_e32 v196, v196, v200
	s_waitcnt lgkmcnt(0)
	v_add_f32_e32 v198, v198, v201
	ds_bpermute_b32 v200, v146, v196
	ds_bpermute_b32 v201, v146, v198
	s_waitcnt lgkmcnt(1)
	v_add_f32_e32 v196, v196, v200
	s_waitcnt lgkmcnt(0)
	v_add_f32_e32 v198, v198, v201
	ds_bpermute_b32 v200, v147, v196
	ds_bpermute_b32 v201, v147, v198
	s_waitcnt lgkmcnt(1)
	v_add_f32_e32 v196, v196, v200
	s_waitcnt lgkmcnt(0)
	v_add_f32_e32 v198, v198, v201
	ds_bpermute_b32 v200, v148, v196
	ds_bpermute_b32 v201, v148, v198
	s_waitcnt lgkmcnt(1)
	v_add_f32_e32 v196, v196, v200
	s_waitcnt lgkmcnt(0)
	v_add_f32_e32 v198, v198, v201
	ds_bpermute_b32 v200, v149, v196
	ds_bpermute_b32 v201, v149, v198
	s_waitcnt lgkmcnt(1)
	v_add_f32_e32 v196, v196, v200
	s_waitcnt lgkmcnt(0)
	v_add_f32_e32 v198, v198, v201
	v_mov_b32_e32 v200, 0x358637bd
	v_fmamk_f32 v196, v196, 0x3a800000, v200
	v_fmamk_f32 v198, v198, 0x3a800000, v200
	v_rsq_f32_e32 v202, v196
	v_rsq_f32_e32 v204, v198
	s_add_u32 s16, s16, 0x2000
	s_addc_u32 s17, s17, 0
	v_pk_mul_f32 v[164:165], v[164:165], v[202:203] op_sel_hi:[1,0]
	v_pk_mul_f32 v[166:167], v[166:167], v[202:203] op_sel_hi:[1,0]
	v_pk_mul_f32 v[168:169], v[168:169], v[202:203] op_sel_hi:[1,0]
	v_pk_mul_f32 v[170:171], v[170:171], v[202:203] op_sel_hi:[1,0]
	v_pk_mul_f32 v[172:173], v[172:173], v[202:203] op_sel_hi:[1,0]
	v_pk_mul_f32 v[174:175], v[174:175], v[202:203] op_sel_hi:[1,0]
	v_pk_mul_f32 v[176:177], v[176:177], v[202:203] op_sel_hi:[1,0]
	v_pk_mul_f32 v[178:179], v[178:179], v[202:203] op_sel_hi:[1,0]
	v_pk_mul_f32 v[164:165], v[128:129], v[164:165]
	v_pk_mul_f32 v[166:167], v[130:131], v[166:167]
	v_pk_mul_f32 v[168:169], v[132:133], v[168:169]
	v_pk_mul_f32 v[170:171], v[134:135], v[170:171]
	v_pk_mul_f32 v[172:173], v[136:137], v[172:173]
	v_pk_mul_f32 v[174:175], v[138:139], v[174:175]
	v_pk_mul_f32 v[176:177], v[140:141], v[176:177]
	v_pk_mul_f32 v[178:179], v[142:143], v[178:179]
	global_store_dwordx4 v151, v[164:167], s[16:17] offset:-4096 nt
	global_store_dwordx4 v151, v[168:171], s[16:17] offset:-4080 nt
	global_store_dwordx4 v151, v[172:175], s[16:17] offset:-2048 nt
	global_store_dwordx4 v151, v[176:179], s[16:17] offset:-2032 nt
	v_pk_mul_f32 v[180:181], v[180:181], v[204:205] op_sel_hi:[1,0]
	v_pk_mul_f32 v[182:183], v[182:183], v[204:205] op_sel_hi:[1,0]
	v_pk_mul_f32 v[184:185], v[184:185], v[204:205] op_sel_hi:[1,0]
	v_pk_mul_f32 v[186:187], v[186:187], v[204:205] op_sel_hi:[1,0]
	v_pk_mul_f32 v[188:189], v[188:189], v[204:205] op_sel_hi:[1,0]
	v_pk_mul_f32 v[190:191], v[190:191], v[204:205] op_sel_hi:[1,0]
	v_pk_mul_f32 v[192:193], v[192:193], v[204:205] op_sel_hi:[1,0]
	v_pk_mul_f32 v[194:195], v[194:195], v[204:205] op_sel_hi:[1,0]
	v_pk_mul_f32 v[180:181], v[128:129], v[180:181]
	v_pk_mul_f32 v[182:183], v[130:131], v[182:183]
	v_pk_mul_f32 v[184:185], v[132:133], v[184:185]
	v_pk_mul_f32 v[186:187], v[134:135], v[186:187]
	v_pk_mul_f32 v[188:189], v[136:137], v[188:189]
	v_pk_mul_f32 v[190:191], v[138:139], v[190:191]
	v_pk_mul_f32 v[192:193], v[140:141], v[192:193]
	v_pk_mul_f32 v[194:195], v[142:143], v[194:195]
	global_store_dwordx4 v151, v[180:183], s[16:17] offset:0 nt
	global_store_dwordx4 v151, v[184:187], s[16:17] offset:16 nt
	global_store_dwordx4 v151, v[188:191], s[16:17] offset:2048 nt
	global_store_dwordx4 v151, v[192:195], s[16:17] offset:2064 nt
	s_waitcnt vmcnt(54)
	v_lshlrev_b32_e32 v164, 16, v96
	v_and_b32_e32 v165, 0xffff0000, v96
	v_lshlrev_b32_e32 v166, 16, v97
	v_and_b32_e32 v167, 0xffff0000, v97
	v_lshlrev_b32_e32 v168, 16, v98
	v_and_b32_e32 v169, 0xffff0000, v98
	v_lshlrev_b32_e32 v170, 16, v99
	v_and_b32_e32 v171, 0xffff0000, v99
	v_lshlrev_b32_e32 v172, 16, v100
	v_and_b32_e32 v173, 0xffff0000, v100
	v_lshlrev_b32_e32 v174, 16, v101
	v_and_b32_e32 v175, 0xffff0000, v101
	v_lshlrev_b32_e32 v176, 16, v102
	v_and_b32_e32 v177, 0xffff0000, v102
	v_lshlrev_b32_e32 v178, 16, v103
	v_and_b32_e32 v179, 0xffff0000, v103
	s_waitcnt vmcnt(52)
	v_lshlrev_b32_e32 v180, 16, v104
	v_and_b32_e32 v181, 0xffff0000, v104
	v_lshlrev_b32_e32 v182, 16, v105
	v_and_b32_e32 v183, 0xffff0000, v105
	v_lshlrev_b32_e32 v184, 16, v106
	v_and_b32_e32 v185, 0xffff0000, v106
	v_lshlrev_b32_e32 v186, 16, v107
	v_and_b32_e32 v187, 0xffff0000, v107
	v_lshlrev_b32_e32 v188, 16, v108
	v_and_b32_e32 v189, 0xffff0000, v108
	v_lshlrev_b32_e32 v190, 16, v109
	v_and_b32_e32 v191, 0xffff0000, v109
	v_lshlrev_b32_e32 v192, 16, v110
	v_and_b32_e32 v193, 0xffff0000, v110
	v_lshlrev_b32_e32 v194, 16, v111
	v_and_b32_e32 v195, 0xffff0000, v111
	v_pk_mul_f32 v[196:197], v[164:165], v[164:165]
	v_pk_mul_f32 v[198:199], v[180:181], v[180:181]
	v_pk_fma_f32 v[196:197], v[166:167], v[166:167], v[196:197]
	v_pk_fma_f32 v[198:199], v[182:183], v[182:183], v[198:199]
	v_pk_fma_f32 v[196:197], v[168:169], v[168:169], v[196:197]
	v_pk_fma_f32 v[198:199], v[184:185], v[184:185], v[198:199]
	v_pk_fma_f32 v[196:197], v[170:171], v[170:171], v[196:197]
	v_pk_fma_f32 v[198:199], v[186:187], v[186:187], v[198:199]
	v_pk_fma_f32 v[196:197], v[172:173], v[172:173], v[196:197]
	v_pk_fma_f32 v[198:199], v[188:189], v[188:189], v[198:199]
	v_pk_fma_f32 v[196:197], v[174:175], v[174:175], v[196:197]
	v_pk_fma_f32 v[198:199], v[190:191], v[190:191], v[198:199]
	v_pk_fma_f32 v[196:197], v[176:177], v[176:177], v[196:197]
	v_pk_fma_f32 v[198:199], v[192:193], v[192:193], v[198:199]
	v_pk_fma_f32 v[196:197], v[178:179], v[178:179], v[196:197]
	v_pk_fma_f32 v[198:199], v[194:195], v[194:195], v[198:199]
	v_add_f32_e32 v196, v196, v197
	v_add_f32_e32 v198, v198, v199
	ds_bpermute_b32 v200, v144, v196
	ds_bpermute_b32 v201, v144, v198
	s_waitcnt lgkmcnt(1)
	v_add_f32_e32 v196, v196, v200
	s_waitcnt lgkmcnt(0)
	v_add_f32_e32 v198, v198, v201
	ds_bpermute_b32 v200, v145, v196
	ds_bpermute_b32 v201, v145, v198
	s_waitcnt lgkmcnt(1)
	v_add_f32_e32 v196, v196, v200
	s_waitcnt lgkmcnt(0)
	v_add_f32_e32 v198, v198, v201
	ds_bpermute_b32 v200, v146, v196
	ds_bpermute_b32 v201, v146, v198
	s_waitcnt lgkmcnt(1)
	v_add_f32_e32 v196, v196, v200
	s_waitcnt lgkmcnt(0)
	v_add_f32_e32 v198, v198, v201
	ds_bpermute_b32 v200, v147, v196
	ds_bpermute_b32 v201, v147, v198
	s_waitcnt lgkmcnt(1)
	v_add_f32_e32 v196, v196, v200
	s_waitcnt lgkmcnt(0)
	v_add_f32_e32 v198, v198, v201
	ds_bpermute_b32 v200, v148, v196
	ds_bpermute_b32 v201, v148, v198
	s_waitcnt lgkmcnt(1)
	v_add_f32_e32 v196, v196, v200
	s_waitcnt lgkmcnt(0)
	v_add_f32_e32 v198, v198, v201
	ds_bpermute_b32 v200, v149, v196
	ds_bpermute_b32 v201, v149, v198
	s_waitcnt lgkmcnt(1)
	v_add_f32_e32 v196, v196, v200
	s_waitcnt lgkmcnt(0)
	v_add_f32_e32 v198, v198, v201
	v_mov_b32_e32 v200, 0x358637bd
	v_fmamk_f32 v196, v196, 0x3a800000, v200
	v_fmamk_f32 v198, v198, 0x3a800000, v200
	v_rsq_f32_e32 v202, v196
	v_rsq_f32_e32 v204, v198
	s_add_u32 s16, s16, 0x2000
	s_addc_u32 s17, s17, 0
	v_pk_mul_f32 v[164:165], v[164:165], v[202:203] op_sel_hi:[1,0]
	v_pk_mul_f32 v[166:167], v[166:167], v[202:203] op_sel_hi:[1,0]
	v_pk_mul_f32 v[168:169], v[168:169], v[202:203] op_sel_hi:[1,0]
	v_pk_mul_f32 v[170:171], v[170:171], v[202:203] op_sel_hi:[1,0]
	v_pk_mul_f32 v[172:173], v[172:173], v[202:203] op_sel_hi:[1,0]
	v_pk_mul_f32 v[174:175], v[174:175], v[202:203] op_sel_hi:[1,0]
	v_pk_mul_f32 v[176:177], v[176:177], v[202:203] op_sel_hi:[1,0]
	v_pk_mul_f32 v[178:179], v[178:179], v[202:203] op_sel_hi:[1,0]
	v_pk_mul_f32 v[164:165], v[128:129], v[164:165]
	v_pk_mul_f32 v[166:167], v[130:131], v[166:167]
	v_pk_mul_f32 v[168:169], v[132:133], v[168:169]
	v_pk_mul_f32 v[170:171], v[134:135], v[170:171]
	v_pk_mul_f32 v[172:173], v[136:137], v[172:173]
	v_pk_mul_f32 v[174:175], v[138:139], v[174:175]
	v_pk_mul_f32 v[176:177], v[140:141], v[176:177]
	v_pk_mul_f32 v[178:179], v[142:143], v[178:179]
	global_store_dwordx4 v151, v[164:167], s[16:17] offset:-4096 nt
	global_store_dwordx4 v151, v[168:171], s[16:17] offset:-4080 nt
	global_store_dwordx4 v151, v[172:175], s[16:17] offset:-2048 nt
	global_store_dwordx4 v151, v[176:179], s[16:17] offset:-2032 nt
	v_pk_mul_f32 v[180:181], v[180:181], v[204:205] op_sel_hi:[1,0]
	v_pk_mul_f32 v[182:183], v[182:183], v[204:205] op_sel_hi:[1,0]
	v_pk_mul_f32 v[184:185], v[184:185], v[204:205] op_sel_hi:[1,0]
	v_pk_mul_f32 v[186:187], v[186:187], v[204:205] op_sel_hi:[1,0]
	v_pk_mul_f32 v[188:189], v[188:189], v[204:205] op_sel_hi:[1,0]
	v_pk_mul_f32 v[190:191], v[190:191], v[204:205] op_sel_hi:[1,0]
	v_pk_mul_f32 v[192:193], v[192:193], v[204:205] op_sel_hi:[1,0]
	v_pk_mul_f32 v[194:195], v[194:195], v[204:205] op_sel_hi:[1,0]
	v_pk_mul_f32 v[180:181], v[128:129], v[180:181]
	v_pk_mul_f32 v[182:183], v[130:131], v[182:183]
	v_pk_mul_f32 v[184:185], v[132:133], v[184:185]
	v_pk_mul_f32 v[186:187], v[134:135], v[186:187]
	v_pk_mul_f32 v[188:189], v[136:137], v[188:189]
	v_pk_mul_f32 v[190:191], v[138:139], v[190:191]
	v_pk_mul_f32 v[192:193], v[140:141], v[192:193]
	v_pk_mul_f32 v[194:195], v[142:143], v[194:195]
	global_store_dwordx4 v151, v[180:183], s[16:17] offset:0 nt
	global_store_dwordx4 v151, v[184:187], s[16:17] offset:16 nt
	global_store_dwordx4 v151, v[188:191], s[16:17] offset:2048 nt
	global_store_dwordx4 v151, v[192:195], s[16:17] offset:2064 nt
	s_waitcnt vmcnt(58)
	v_lshlrev_b32_e32 v164, 16, v112
	v_and_b32_e32 v165, 0xffff0000, v112
	v_lshlrev_b32_e32 v166, 16, v113
	v_and_b32_e32 v167, 0xffff0000, v113
	v_lshlrev_b32_e32 v168, 16, v114
	v_and_b32_e32 v169, 0xffff0000, v114
	v_lshlrev_b32_e32 v170, 16, v115
	v_and_b32_e32 v171, 0xffff0000, v115
	v_lshlrev_b32_e32 v172, 16, v116
	v_and_b32_e32 v173, 0xffff0000, v116
	v_lshlrev_b32_e32 v174, 16, v117
	v_and_b32_e32 v175, 0xffff0000, v117
	v_lshlrev_b32_e32 v176, 16, v118
	v_and_b32_e32 v177, 0xffff0000, v118
	v_lshlrev_b32_e32 v178, 16, v119
	v_and_b32_e32 v179, 0xffff0000, v119
	s_waitcnt vmcnt(56)
	v_lshlrev_b32_e32 v180, 16, v120
	v_and_b32_e32 v181, 0xffff0000, v120
	v_lshlrev_b32_e32 v182, 16, v121
	v_and_b32_e32 v183, 0xffff0000, v121
	v_lshlrev_b32_e32 v184, 16, v122
	v_and_b32_e32 v185, 0xffff0000, v122
	v_lshlrev_b32_e32 v186, 16, v123
	v_and_b32_e32 v187, 0xffff0000, v123
	v_lshlrev_b32_e32 v188, 16, v124
	v_and_b32_e32 v189, 0xffff0000, v124
	v_lshlrev_b32_e32 v190, 16, v125
	v_and_b32_e32 v191, 0xffff0000, v125
	v_lshlrev_b32_e32 v192, 16, v126
	v_and_b32_e32 v193, 0xffff0000, v126
	v_lshlrev_b32_e32 v194, 16, v127
	v_and_b32_e32 v195, 0xffff0000, v127
	v_pk_mul_f32 v[196:197], v[164:165], v[164:165]
	v_pk_mul_f32 v[198:199], v[180:181], v[180:181]
	v_pk_fma_f32 v[196:197], v[166:167], v[166:167], v[196:197]
	v_pk_fma_f32 v[198:199], v[182:183], v[182:183], v[198:199]
	v_pk_fma_f32 v[196:197], v[168:169], v[168:169], v[196:197]
	v_pk_fma_f32 v[198:199], v[184:185], v[184:185], v[198:199]
	v_pk_fma_f32 v[196:197], v[170:171], v[170:171], v[196:197]
	v_pk_fma_f32 v[198:199], v[186:187], v[186:187], v[198:199]
	v_pk_fma_f32 v[196:197], v[172:173], v[172:173], v[196:197]
	v_pk_fma_f32 v[198:199], v[188:189], v[188:189], v[198:199]
	v_pk_fma_f32 v[196:197], v[174:175], v[174:175], v[196:197]
	v_pk_fma_f32 v[198:199], v[190:191], v[190:191], v[198:199]
	v_pk_fma_f32 v[196:197], v[176:177], v[176:177], v[196:197]
	v_pk_fma_f32 v[198:199], v[192:193], v[192:193], v[198:199]
	v_pk_fma_f32 v[196:197], v[178:179], v[178:179], v[196:197]
	v_pk_fma_f32 v[198:199], v[194:195], v[194:195], v[198:199]
	v_add_f32_e32 v196, v196, v197
	v_add_f32_e32 v198, v198, v199
	ds_bpermute_b32 v200, v144, v196
	ds_bpermute_b32 v201, v144, v198
	s_waitcnt lgkmcnt(1)
	v_add_f32_e32 v196, v196, v200
	s_waitcnt lgkmcnt(0)
	v_add_f32_e32 v198, v198, v201
	ds_bpermute_b32 v200, v145, v196
	ds_bpermute_b32 v201, v145, v198
	s_waitcnt lgkmcnt(1)
	v_add_f32_e32 v196, v196, v200
	s_waitcnt lgkmcnt(0)
	v_add_f32_e32 v198, v198, v201
	ds_bpermute_b32 v200, v146, v196
	ds_bpermute_b32 v201, v146, v198
	s_waitcnt lgkmcnt(1)
	v_add_f32_e32 v196, v196, v200
	s_waitcnt lgkmcnt(0)
	v_add_f32_e32 v198, v198, v201
	ds_bpermute_b32 v200, v147, v196
	ds_bpermute_b32 v201, v147, v198
	s_waitcnt lgkmcnt(1)
	v_add_f32_e32 v196, v196, v200
	s_waitcnt lgkmcnt(0)
	v_add_f32_e32 v198, v198, v201
	ds_bpermute_b32 v200, v148, v196
	ds_bpermute_b32 v201, v148, v198
	s_waitcnt lgkmcnt(1)
	v_add_f32_e32 v196, v196, v200
	s_waitcnt lgkmcnt(0)
	v_add_f32_e32 v198, v198, v201
	ds_bpermute_b32 v200, v149, v196
	ds_bpermute_b32 v201, v149, v198
	s_waitcnt lgkmcnt(1)
	v_add_f32_e32 v196, v196, v200
	s_waitcnt lgkmcnt(0)
	v_add_f32_e32 v198, v198, v201
	v_mov_b32_e32 v200, 0x358637bd
	v_fmamk_f32 v196, v196, 0x3a800000, v200
	v_fmamk_f32 v198, v198, 0x3a800000, v200
	v_rsq_f32_e32 v202, v196
	v_rsq_f32_e32 v204, v198
	s_add_u32 s16, s16, 0x2000
	s_addc_u32 s17, s17, 0
	v_pk_mul_f32 v[164:165], v[164:165], v[202:203] op_sel_hi:[1,0]
	v_pk_mul_f32 v[166:167], v[166:167], v[202:203] op_sel_hi:[1,0]
	v_pk_mul_f32 v[168:169], v[168:169], v[202:203] op_sel_hi:[1,0]
	v_pk_mul_f32 v[170:171], v[170:171], v[202:203] op_sel_hi:[1,0]
	v_pk_mul_f32 v[172:173], v[172:173], v[202:203] op_sel_hi:[1,0]
	v_pk_mul_f32 v[174:175], v[174:175], v[202:203] op_sel_hi:[1,0]
	v_pk_mul_f32 v[176:177], v[176:177], v[202:203] op_sel_hi:[1,0]
	v_pk_mul_f32 v[178:179], v[178:179], v[202:203] op_sel_hi:[1,0]
	v_pk_mul_f32 v[164:165], v[128:129], v[164:165]
	v_pk_mul_f32 v[166:167], v[130:131], v[166:167]
	v_pk_mul_f32 v[168:169], v[132:133], v[168:169]
	v_pk_mul_f32 v[170:171], v[134:135], v[170:171]
	v_pk_mul_f32 v[172:173], v[136:137], v[172:173]
	v_pk_mul_f32 v[174:175], v[138:139], v[174:175]
	v_pk_mul_f32 v[176:177], v[140:141], v[176:177]
	v_pk_mul_f32 v[178:179], v[142:143], v[178:179]
	global_store_dwordx4 v151, v[164:167], s[16:17] offset:-4096 nt
	global_store_dwordx4 v151, v[168:171], s[16:17] offset:-4080 nt
	global_store_dwordx4 v151, v[172:175], s[16:17] offset:-2048 nt
	global_store_dwordx4 v151, v[176:179], s[16:17] offset:-2032 nt
	v_pk_mul_f32 v[180:181], v[180:181], v[204:205] op_sel_hi:[1,0]
	v_pk_mul_f32 v[182:183], v[182:183], v[204:205] op_sel_hi:[1,0]
	v_pk_mul_f32 v[184:185], v[184:185], v[204:205] op_sel_hi:[1,0]
	v_pk_mul_f32 v[186:187], v[186:187], v[204:205] op_sel_hi:[1,0]
	v_pk_mul_f32 v[188:189], v[188:189], v[204:205] op_sel_hi:[1,0]
	v_pk_mul_f32 v[190:191], v[190:191], v[204:205] op_sel_hi:[1,0]
	v_pk_mul_f32 v[192:193], v[192:193], v[204:205] op_sel_hi:[1,0]
	v_pk_mul_f32 v[194:195], v[194:195], v[204:205] op_sel_hi:[1,0]
	v_pk_mul_f32 v[180:181], v[128:129], v[180:181]
	v_pk_mul_f32 v[182:183], v[130:131], v[182:183]
	v_pk_mul_f32 v[184:185], v[132:133], v[184:185]
	v_pk_mul_f32 v[186:187], v[134:135], v[186:187]
	v_pk_mul_f32 v[188:189], v[136:137], v[188:189]
	v_pk_mul_f32 v[190:191], v[138:139], v[190:191]
	v_pk_mul_f32 v[192:193], v[140:141], v[192:193]
	v_pk_mul_f32 v[194:195], v[142:143], v[194:195]
	global_store_dwordx4 v151, v[180:183], s[16:17] offset:0 nt
	global_store_dwordx4 v151, v[184:187], s[16:17] offset:16 nt
	global_store_dwordx4 v151, v[188:191], s[16:17] offset:2048 nt
	global_store_dwordx4 v151, v[192:195], s[16:17] offset:2064 nt
	s_add_u32 s10, s10, s12
	s_cmp_lt_u32 s10, 0x800
	s_cbranch_scc1 .Lp20_group

.Lp1_group:
	s_lshr_b32 s24, s25, 9
	s_mul_i32 s24, s24, 0x6000
	s_add_u32 s20, s4, s24
	s_addc_u32 s21, s5, 0
	s_add_u32 s22, s20, 0x1000
	s_addc_u32 s23, s21, 0
	global_load_dwordx4 v[0:3], v178, s[12:13] offset:0
	global_load_dwordx4 v[16:19], v178, s[20:21] offset:0
	global_load_dwordx4 v[128:131], v178, s[22:23] offset:0
	global_load_dwordx4 v[4:7], v178, s[12:13] offset:16
	global_load_dwordx4 v[20:23], v178, s[20:21] offset:16
	global_load_dwordx4 v[132:135], v178, s[22:23] offset:16
	global_load_dwordx4 v[8:11], v178, s[12:13] offset:2048
	global_load_dwordx4 v[24:27], v178, s[20:21] offset:2048
	global_load_dwordx4 v[136:139], v178, s[22:23] offset:2048
	global_load_dwordx4 v[12:15], v178, s[12:13] offset:2064
	global_load_dwordx4 v[28:31], v178, s[20:21] offset:2064
	global_load_dwordx4 v[140:143], v178, s[22:23] offset:2064
	s_lshl_b32 s24, s25, 16
	s_add_u32 s16, s6, s24
	s_addc_u32 s17, s7, 0
	s_add_u32 s16, s16, 0x1000
	s_addc_u32 s17, s17, 0
	s_lshl_b32 s24, s25, 15
	s_add_u32 s24, s24, 0x4000800
	s_add_u32 s18, s4, s24
	s_addc_u32 s19, s5, 0
	global_load_dwordx4 v[32:35], v178, s[16:17] offset:-4096 nt
	global_load_dwordx4 v[36:39], v178, s[16:17] offset:-4080 nt
	global_load_dwordx4 v[40:43], v178, s[16:17] offset:-2048 nt
	global_load_dwordx4 v[44:47], v178, s[16:17] offset:-2032 nt
	global_load_dwordx4 v[48:51], v178, s[16:17] offset:0 nt
	global_load_dwordx4 v[52:55], v178, s[16:17] offset:16 nt
	global_load_dwordx4 v[56:59], v178, s[16:17] offset:2048 nt
	global_load_dwordx4 v[60:63], v178, s[16:17] offset:2064 nt
	s_add_u32 s16, s16, 0x2000
	s_addc_u32 s17, s17, 0
	global_load_dwordx4 v[64:67], v178, s[16:17] offset:-4096 nt
	global_load_dwordx4 v[68:71], v178, s[16:17] offset:-4080 nt
	global_load_dwordx4 v[72:75], v178, s[16:17] offset:-2048 nt
	global_load_dwordx4 v[76:79], v178, s[16:17] offset:-2032 nt
	global_load_dwordx4 v[80:83], v178, s[16:17] offset:0 nt
	global_load_dwordx4 v[84:87], v178, s[16:17] offset:16 nt
	global_load_dwordx4 v[88:91], v178, s[16:17] offset:2048 nt
	global_load_dwordx4 v[92:95], v178, s[16:17] offset:2064 nt
	s_add_u32 s16, s16, 0x2000
	s_addc_u32 s17, s17, 0
	global_load_dwordx4 v[96:99], v178, s[16:17] offset:-4096 nt
	global_load_dwordx4 v[100:103], v178, s[16:17] offset:-4080 nt
	global_load_dwordx4 v[104:107], v178, s[16:17] offset:-2048 nt
	global_load_dwordx4 v[108:111], v178, s[16:17] offset:-2032 nt
	global_load_dwordx4 v[112:115], v178, s[16:17] offset:0 nt
	global_load_dwordx4 v[116:119], v178, s[16:17] offset:16 nt
	global_load_dwordx4 v[120:123], v178, s[16:17] offset:2048 nt
	global_load_dwordx4 v[124:127], v178, s[16:17] offset:2064 nt
	s_waitcnt vmcnt(24)
	v_add_f32_e32 v128, 1.0, v128
	v_add_f32_e32 v129, 1.0, v129
	v_add_f32_e32 v130, 1.0, v130
	v_add_f32_e32 v131, 1.0, v131
	v_add_f32_e32 v132, 1.0, v132
	v_add_f32_e32 v133, 1.0, v133
	v_add_f32_e32 v134, 1.0, v134
	v_add_f32_e32 v135, 1.0, v135
	v_add_f32_e32 v136, 1.0, v136
	v_add_f32_e32 v137, 1.0, v137
	v_add_f32_e32 v138, 1.0, v138
	v_add_f32_e32 v139, 1.0, v139
	v_add_f32_e32 v140, 1.0, v140
	v_add_f32_e32 v141, 1.0, v141
	v_add_f32_e32 v142, 1.0, v142
	v_add_f32_e32 v143, 1.0, v143
	v_mul_f32_e32 v0, v0, v128
	v_mul_f32_e32 v1, v1, v129
	v_mul_f32_e32 v2, v2, v130
	v_mul_f32_e32 v3, v3, v131
	v_mul_f32_e32 v4, v4, v132
	v_mul_f32_e32 v5, v5, v133
	v_mul_f32_e32 v6, v6, v134
	v_mul_f32_e32 v7, v7, v135
	v_mul_f32_e32 v8, v8, v136
	v_mul_f32_e32 v9, v9, v137
	v_mul_f32_e32 v10, v10, v138
	v_mul_f32_e32 v11, v11, v139
	v_mul_f32_e32 v12, v12, v140
	v_mul_f32_e32 v13, v13, v141
	v_mul_f32_e32 v14, v14, v142
	v_mul_f32_e32 v15, v15, v143
	s_waitcnt vmcnt(16)
	v_pk_mul_f32 v[180:181], v[32:33], v[32:33]
	v_pk_mul_f32 v[182:183], v[48:49], v[48:49]
	v_pk_fma_f32 v[180:181], v[34:35], v[34:35], v[180:181]
	v_pk_fma_f32 v[182:183], v[50:51], v[50:51], v[182:183]
	v_pk_fma_f32 v[180:181], v[36:37], v[36:37], v[180:181]
	v_pk_fma_f32 v[182:183], v[52:53], v[52:53], v[182:183]
	v_pk_fma_f32 v[180:181], v[38:39], v[38:39], v[180:181]
	v_pk_fma_f32 v[182:183], v[54:55], v[54:55], v[182:183]
	v_pk_fma_f32 v[180:181], v[40:41], v[40:41], v[180:181]
	v_pk_fma_f32 v[182:183], v[56:57], v[56:57], v[182:183]
	v_pk_fma_f32 v[180:181], v[42:43], v[42:43], v[180:181]
	v_pk_fma_f32 v[182:183], v[58:59], v[58:59], v[182:183]
	v_pk_fma_f32 v[180:181], v[44:45], v[44:45], v[180:181]
	v_pk_fma_f32 v[182:183], v[60:61], v[60:61], v[182:183]
	v_pk_fma_f32 v[180:181], v[46:47], v[46:47], v[180:181]
	v_pk_fma_f32 v[182:183], v[62:63], v[62:63], v[182:183]
	v_add_f32_e32 v180, v180, v181
	v_add_f32_e32 v182, v182, v183
	ds_bpermute_b32 v184, v172, v180
	ds_bpermute_b32 v185, v172, v182
	s_waitcnt lgkmcnt(1)
	v_add_f32_e32 v180, v180, v184
	s_waitcnt lgkmcnt(0)
	v_add_f32_e32 v182, v182, v185
	ds_bpermute_b32 v184, v173, v180
	ds_bpermute_b32 v185, v173, v182
	s_waitcnt lgkmcnt(1)
	v_add_f32_e32 v180, v180, v184
	s_waitcnt lgkmcnt(0)
	v_add_f32_e32 v182, v182, v185
	ds_bpermute_b32 v184, v174, v180
	ds_bpermute_b32 v185, v174, v182
	s_waitcnt lgkmcnt(1)
	v_add_f32_e32 v180, v180, v184
	s_waitcnt lgkmcnt(0)
	v_add_f32_e32 v182, v182, v185
	ds_bpermute_b32 v184, v175, v180
	ds_bpermute_b32 v185, v175, v182
	s_waitcnt lgkmcnt(1)
	v_add_f32_e32 v180, v180, v184
	s_waitcnt lgkmcnt(0)
	v_add_f32_e32 v182, v182, v185
	ds_bpermute_b32 v184, v176, v180
	ds_bpermute_b32 v185, v176, v182
	s_waitcnt lgkmcnt(1)
	v_add_f32_e32 v180, v180, v184
	s_waitcnt lgkmcnt(0)
	v_add_f32_e32 v182, v182, v185
	ds_bpermute_b32 v184, v177, v180
	ds_bpermute_b32 v185, v177, v182
	s_waitcnt lgkmcnt(1)
	v_add_f32_e32 v180, v180, v184
	s_waitcnt lgkmcnt(0)
	v_add_f32_e32 v182, v182, v185
	v_mov_b32_e32 v184, 0x358637bd
	v_fmamk_f32 v180, v180, 0x3a800000, v184
	v_fmamk_f32 v182, v182, 0x3a800000, v184
	v_rsq_f32_e32 v186, v180
	v_rsq_f32_e32 v188, v182
	v_pk_mul_f32 v[32:33], v[32:33], v[186:187] op_sel_hi:[1,0]
	v_pk_mul_f32 v[34:35], v[34:35], v[186:187] op_sel_hi:[1,0]
	v_pk_mul_f32 v[36:37], v[36:37], v[186:187] op_sel_hi:[1,0]
	v_pk_mul_f32 v[38:39], v[38:39], v[186:187] op_sel_hi:[1,0]
	v_pk_mul_f32 v[40:41], v[40:41], v[186:187] op_sel_hi:[1,0]
	v_pk_mul_f32 v[42:43], v[42:43], v[186:187] op_sel_hi:[1,0]
	v_pk_mul_f32 v[44:45], v[44:45], v[186:187] op_sel_hi:[1,0]
	v_pk_mul_f32 v[46:47], v[46:47], v[186:187] op_sel_hi:[1,0]
	v_pk_mul_f32 v[48:49], v[48:49], v[188:189] op_sel_hi:[1,0]
	v_pk_mul_f32 v[50:51], v[50:51], v[188:189] op_sel_hi:[1,0]
	v_pk_mul_f32 v[52:53], v[52:53], v[188:189] op_sel_hi:[1,0]
	v_pk_mul_f32 v[54:55], v[54:55], v[188:189] op_sel_hi:[1,0]
	v_pk_mul_f32 v[56:57], v[56:57], v[188:189] op_sel_hi:[1,0]
	v_pk_mul_f32 v[58:59], v[58:59], v[188:189] op_sel_hi:[1,0]
	v_pk_mul_f32 v[60:61], v[60:61], v[188:189] op_sel_hi:[1,0]
	v_pk_mul_f32 v[62:63], v[62:63], v[188:189] op_sel_hi:[1,0]
	v_pk_fma_f32 v[32:33], v[32:33], v[0:1], v[16:17]
	v_pk_fma_f32 v[34:35], v[34:35], v[2:3], v[18:19]
	v_pk_fma_f32 v[36:37], v[36:37], v[4:5], v[20:21]
	v_pk_fma_f32 v[38:39], v[38:39], v[6:7], v[22:23]
	v_pk_fma_f32 v[40:41], v[40:41], v[8:9], v[24:25]
	v_pk_fma_f32 v[42:43], v[42:43], v[10:11], v[26:27]
	v_pk_fma_f32 v[44:45], v[44:45], v[12:13], v[28:29]
	v_pk_fma_f32 v[46:47], v[46:47], v[14:15], v[30:31]
	v_pk_fma_f32 v[48:49], v[48:49], v[0:1], v[16:17]
	v_pk_fma_f32 v[50:51], v[50:51], v[2:3], v[18:19]
	v_pk_fma_f32 v[52:53], v[52:53], v[4:5], v[20:21]
	v_pk_fma_f32 v[54:55], v[54:55], v[6:7], v[22:23]
	v_pk_fma_f32 v[56:57], v[56:57], v[8:9], v[24:25]
	v_pk_fma_f32 v[58:59], v[58:59], v[10:11], v[26:27]
	v_pk_fma_f32 v[60:61], v[60:61], v[12:13], v[28:29]
	v_pk_fma_f32 v[62:63], v[62:63], v[14:15], v[30:31]
	v_cvt_pk_bf16_f32 v144, v32, v33
	v_cvt_pk_bf16_f32 v145, v34, v35
	v_cvt_pk_bf16_f32 v146, v36, v37
	v_cvt_pk_bf16_f32 v147, v38, v39
	v_cvt_pk_bf16_f32 v148, v40, v41
	v_cvt_pk_bf16_f32 v149, v42, v43
	v_cvt_pk_bf16_f32 v150, v44, v45
	v_cvt_pk_bf16_f32 v151, v46, v47
	v_cvt_pk_bf16_f32 v164, v48, v49
	v_cvt_pk_bf16_f32 v165, v50, v51
	v_cvt_pk_bf16_f32 v166, v52, v53
	v_cvt_pk_bf16_f32 v167, v54, v55
	v_cvt_pk_bf16_f32 v168, v56, v57
	v_cvt_pk_bf16_f32 v169, v58, v59
	v_cvt_pk_bf16_f32 v170, v60, v61
	v_cvt_pk_bf16_f32 v171, v62, v63
	global_store_dwordx4 v179, v[144:147], s[18:19] offset:-2048
	global_store_dwordx4 v179, v[148:151], s[18:19] offset:-1024
	global_store_dwordx4 v179, v[164:167], s[18:19] offset:0
	global_store_dwordx4 v179, v[168:171], s[18:19] offset:1024
	s_add_u32 s16, s16, 0x2000
	s_addc_u32 s17, s17, 0
	global_load_dwordx4 v[32:35], v178, s[16:17] offset:-4096 nt
	global_load_dwordx4 v[36:39], v178, s[16:17] offset:-4080 nt
	global_load_dwordx4 v[40:43], v178, s[16:17] offset:-2048 nt
	global_load_dwordx4 v[44:47], v178, s[16:17] offset:-2032 nt
	global_load_dwordx4 v[48:51], v178, s[16:17] offset:0 nt
	global_load_dwordx4 v[52:55], v178, s[16:17] offset:16 nt
	global_load_dwordx4 v[56:59], v178, s[16:17] offset:2048 nt
	global_load_dwordx4 v[60:63], v178, s[16:17] offset:2064 nt
	s_waitcnt vmcnt(20)
	v_pk_mul_f32 v[180:181], v[64:65], v[64:65]
	v_pk_mul_f32 v[182:183], v[80:81], v[80:81]
	v_pk_fma_f32 v[180:181], v[66:67], v[66:67], v[180:181]
	v_pk_fma_f32 v[182:183], v[82:83], v[82:83], v[182:183]
	v_pk_fma_f32 v[180:181], v[68:69], v[68:69], v[180:181]
	v_pk_fma_f32 v[182:183], v[84:85], v[84:85], v[182:183]
	v_pk_fma_f32 v[180:181], v[70:71], v[70:71], v[180:181]
	v_pk_fma_f32 v[182:183], v[86:87], v[86:87], v[182:183]
	v_pk_fma_f32 v[180:181], v[72:73], v[72:73], v[180:181]
	v_pk_fma_f32 v[182:183], v[88:89], v[88:89], v[182:183]
	v_pk_fma_f32 v[180:181], v[74:75], v[74:75], v[180:181]
	v_pk_fma_f32 v[182:183], v[90:91], v[90:91], v[182:183]
	v_pk_fma_f32 v[180:181], v[76:77], v[76:77], v[180:181]
	v_pk_fma_f32 v[182:183], v[92:93], v[92:93], v[182:183]
	v_pk_fma_f32 v[180:181], v[78:79], v[78:79], v[180:181]
	v_pk_fma_f32 v[182:183], v[94:95], v[94:95], v[182:183]
	v_add_f32_e32 v180, v180, v181
	v_add_f32_e32 v182, v182, v183
	ds_bpermute_b32 v184, v172, v180
	ds_bpermute_b32 v185, v172, v182
	s_waitcnt lgkmcnt(1)
	v_add_f32_e32 v180, v180, v184
	s_waitcnt lgkmcnt(0)
	v_add_f32_e32 v182, v182, v185
	ds_bpermute_b32 v184, v173, v180
	ds_bpermute_b32 v185, v173, v182
	s_waitcnt lgkmcnt(1)
	v_add_f32_e32 v180, v180, v184
	s_waitcnt lgkmcnt(0)
	v_add_f32_e32 v182, v182, v185
	ds_bpermute_b32 v184, v174, v180
	ds_bpermute_b32 v185, v174, v182
	s_waitcnt lgkmcnt(1)
	v_add_f32_e32 v180, v180, v184
	s_waitcnt lgkmcnt(0)
	v_add_f32_e32 v182, v182, v185
	ds_bpermute_b32 v184, v175, v180
	ds_bpermute_b32 v185, v175, v182
	s_waitcnt lgkmcnt(1)
	v_add_f32_e32 v180, v180, v184
	s_waitcnt lgkmcnt(0)
	v_add_f32_e32 v182, v182, v185
	ds_bpermute_b32 v184, v176, v180
	ds_bpermute_b32 v185, v176, v182
	s_waitcnt lgkmcnt(1)
	v_add_f32_e32 v180, v180, v184
	s_waitcnt lgkmcnt(0)
	v_add_f32_e32 v182, v182, v185
	ds_bpermute_b32 v184, v177, v180
	ds_bpermute_b32 v185, v177, v182
	s_waitcnt lgkmcnt(1)
	v_add_f32_e32 v180, v180, v184
	s_waitcnt lgkmcnt(0)
	v_add_f32_e32 v182, v182, v185
	v_mov_b32_e32 v184, 0x358637bd
	v_fmamk_f32 v180, v180, 0x3a800000, v184
	v_fmamk_f32 v182, v182, 0x3a800000, v184
	v_rsq_f32_e32 v186, v180
	v_rsq_f32_e32 v188, v182
	v_pk_mul_f32 v[64:65], v[64:65], v[186:187] op_sel_hi:[1,0]
	v_pk_mul_f32 v[66:67], v[66:67], v[186:187] op_sel_hi:[1,0]
	v_pk_mul_f32 v[68:69], v[68:69], v[186:187] op_sel_hi:[1,0]
	v_pk_mul_f32 v[70:71], v[70:71], v[186:187] op_sel_hi:[1,0]
	v_pk_mul_f32 v[72:73], v[72:73], v[186:187] op_sel_hi:[1,0]
	v_pk_mul_f32 v[74:75], v[74:75], v[186:187] op_sel_hi:[1,0]
	v_pk_mul_f32 v[76:77], v[76:77], v[186:187] op_sel_hi:[1,0]
	v_pk_mul_f32 v[78:79], v[78:79], v[186:187] op_sel_hi:[1,0]
	v_pk_mul_f32 v[80:81], v[80:81], v[188:189] op_sel_hi:[1,0]
	v_pk_mul_f32 v[82:83], v[82:83], v[188:189] op_sel_hi:[1,0]
	v_pk_mul_f32 v[84:85], v[84:85], v[188:189] op_sel_hi:[1,0]
	v_pk_mul_f32 v[86:87], v[86:87], v[188:189] op_sel_hi:[1,0]
	v_pk_mul_f32 v[88:89], v[88:89], v[188:189] op_sel_hi:[1,0]
	v_pk_mul_f32 v[90:91], v[90:91], v[188:189] op_sel_hi:[1,0]
	v_pk_mul_f32 v[92:93], v[92:93], v[188:189] op_sel_hi:[1,0]
	v_pk_mul_f32 v[94:95], v[94:95], v[188:189] op_sel_hi:[1,0]
	v_pk_fma_f32 v[64:65], v[64:65], v[0:1], v[16:17]
	v_pk_fma_f32 v[66:67], v[66:67], v[2:3], v[18:19]
	v_pk_fma_f32 v[68:69], v[68:69], v[4:5], v[20:21]
	v_pk_fma_f32 v[70:71], v[70:71], v[6:7], v[22:23]
	v_pk_fma_f32 v[72:73], v[72:73], v[8:9], v[24:25]
	v_pk_fma_f32 v[74:75], v[74:75], v[10:11], v[26:27]
	v_pk_fma_f32 v[76:77], v[76:77], v[12:13], v[28:29]
	v_pk_fma_f32 v[78:79], v[78:79], v[14:15], v[30:31]
	v_pk_fma_f32 v[80:81], v[80:81], v[0:1], v[16:17]
	v_pk_fma_f32 v[82:83], v[82:83], v[2:3], v[18:19]
	v_pk_fma_f32 v[84:85], v[84:85], v[4:5], v[20:21]
	v_pk_fma_f32 v[86:87], v[86:87], v[6:7], v[22:23]
	v_pk_fma_f32 v[88:89], v[88:89], v[8:9], v[24:25]
	v_pk_fma_f32 v[90:91], v[90:91], v[10:11], v[26:27]
	v_pk_fma_f32 v[92:93], v[92:93], v[12:13], v[28:29]
	v_pk_fma_f32 v[94:95], v[94:95], v[14:15], v[30:31]
	v_cvt_pk_bf16_f32 v144, v64, v65
	v_cvt_pk_bf16_f32 v145, v66, v67
	v_cvt_pk_bf16_f32 v146, v68, v69
	v_cvt_pk_bf16_f32 v147, v70, v71
	v_cvt_pk_bf16_f32 v148, v72, v73
	v_cvt_pk_bf16_f32 v149, v74, v75
	v_cvt_pk_bf16_f32 v150, v76, v77
	v_cvt_pk_bf16_f32 v151, v78, v79
	v_cvt_pk_bf16_f32 v164, v80, v81
	v_cvt_pk_bf16_f32 v165, v82, v83
	v_cvt_pk_bf16_f32 v166, v84, v85
	v_cvt_pk_bf16_f32 v167, v86, v87
	v_cvt_pk_bf16_f32 v168, v88, v89
	v_cvt_pk_bf16_f32 v169, v90, v91
	v_cvt_pk_bf16_f32 v170, v92, v93
	v_cvt_pk_bf16_f32 v171, v94, v95
	s_add_u32 s18, s18, 0x1000
	s_addc_u32 s19, s19, 0
	global_store_dwordx4 v179, v[144:147], s[18:19] offset:-2048
	global_store_dwordx4 v179, v[148:151], s[18:19] offset:-1024
	global_store_dwordx4 v179, v[164:167], s[18:19] offset:0
	global_store_dwordx4 v179, v[168:171], s[18:19] offset:1024
	s_add_u32 s16, s16, 0x2000
	s_addc_u32 s17, s17, 0
	global_load_dwordx4 v[64:67], v178, s[16:17] offset:-4096 nt
	global_load_dwordx4 v[68:71], v178, s[16:17] offset:-4080 nt
	global_load_dwordx4 v[72:75], v178, s[16:17] offset:-2048 nt
	global_load_dwordx4 v[76:79], v178, s[16:17] offset:-2032 nt
	global_load_dwordx4 v[80:83], v178, s[16:17] offset:0 nt
	global_load_dwordx4 v[84:87], v178, s[16:17] offset:16 nt
	global_load_dwordx4 v[88:91], v178, s[16:17] offset:2048 nt
	global_load_dwordx4 v[92:95], v178, s[16:17] offset:2064 nt
	s_waitcnt vmcnt(24)
	v_pk_mul_f32 v[180:181], v[96:97], v[96:97]
	v_pk_mul_f32 v[182:183], v[112:113], v[112:113]
	v_pk_fma_f32 v[180:181], v[98:99], v[98:99], v[180:181]
	v_pk_fma_f32 v[182:183], v[114:115], v[114:115], v[182:183]
	v_pk_fma_f32 v[180:181], v[100:101], v[100:101], v[180:181]
	v_pk_fma_f32 v[182:183], v[116:117], v[116:117], v[182:183]
	v_pk_fma_f32 v[180:181], v[102:103], v[102:103], v[180:181]
	v_pk_fma_f32 v[182:183], v[118:119], v[118:119], v[182:183]
	v_pk_fma_f32 v[180:181], v[104:105], v[104:105], v[180:181]
	v_pk_fma_f32 v[182:183], v[120:121], v[120:121], v[182:183]
	v_pk_fma_f32 v[180:181], v[106:107], v[106:107], v[180:181]
	v_pk_fma_f32 v[182:183], v[122:123], v[122:123], v[182:183]
	v_pk_fma_f32 v[180:181], v[108:109], v[108:109], v[180:181]
	v_pk_fma_f32 v[182:183], v[124:125], v[124:125], v[182:183]
	v_pk_fma_f32 v[180:181], v[110:111], v[110:111], v[180:181]
	v_pk_fma_f32 v[182:183], v[126:127], v[126:127], v[182:183]
	v_add_f32_e32 v180, v180, v181
	v_add_f32_e32 v182, v182, v183
	ds_bpermute_b32 v184, v172, v180
	ds_bpermute_b32 v185, v172, v182
	s_waitcnt lgkmcnt(1)
	v_add_f32_e32 v180, v180, v184
	s_waitcnt lgkmcnt(0)
	v_add_f32_e32 v182, v182, v185
	ds_bpermute_b32 v184, v173, v180
	ds_bpermute_b32 v185, v173, v182
	s_waitcnt lgkmcnt(1)
	v_add_f32_e32 v180, v180, v184
	s_waitcnt lgkmcnt(0)
	v_add_f32_e32 v182, v182, v185
	ds_bpermute_b32 v184, v174, v180
	ds_bpermute_b32 v185, v174, v182
	s_waitcnt lgkmcnt(1)
	v_add_f32_e32 v180, v180, v184
	s_waitcnt lgkmcnt(0)
	v_add_f32_e32 v182, v182, v185
	ds_bpermute_b32 v184, v175, v180
	ds_bpermute_b32 v185, v175, v182
	s_waitcnt lgkmcnt(1)
	v_add_f32_e32 v180, v180, v184
	s_waitcnt lgkmcnt(0)
	v_add_f32_e32 v182, v182, v185
	ds_bpermute_b32 v184, v176, v180
	ds_bpermute_b32 v185, v176, v182
	s_waitcnt lgkmcnt(1)
	v_add_f32_e32 v180, v180, v184
	s_waitcnt lgkmcnt(0)
	v_add_f32_e32 v182, v182, v185
	ds_bpermute_b32 v184, v177, v180
	ds_bpermute_b32 v185, v177, v182
	s_waitcnt lgkmcnt(1)
	v_add_f32_e32 v180, v180, v184
	s_waitcnt lgkmcnt(0)
	v_add_f32_e32 v182, v182, v185
	v_mov_b32_e32 v184, 0x358637bd
	v_fmamk_f32 v180, v180, 0x3a800000, v184
	v_fmamk_f32 v182, v182, 0x3a800000, v184
	v_rsq_f32_e32 v186, v180
	v_rsq_f32_e32 v188, v182
	v_pk_mul_f32 v[96:97], v[96:97], v[186:187] op_sel_hi:[1,0]
	v_pk_mul_f32 v[98:99], v[98:99], v[186:187] op_sel_hi:[1,0]
	v_pk_mul_f32 v[100:101], v[100:101], v[186:187] op_sel_hi:[1,0]
	v_pk_mul_f32 v[102:103], v[102:103], v[186:187] op_sel_hi:[1,0]
	v_pk_mul_f32 v[104:105], v[104:105], v[186:187] op_sel_hi:[1,0]
	v_pk_mul_f32 v[106:107], v[106:107], v[186:187] op_sel_hi:[1,0]
	v_pk_mul_f32 v[108:109], v[108:109], v[186:187] op_sel_hi:[1,0]
	v_pk_mul_f32 v[110:111], v[110:111], v[186:187] op_sel_hi:[1,0]
	v_pk_mul_f32 v[112:113], v[112:113], v[188:189] op_sel_hi:[1,0]
	v_pk_mul_f32 v[114:115], v[114:115], v[188:189] op_sel_hi:[1,0]
	v_pk_mul_f32 v[116:117], v[116:117], v[188:189] op_sel_hi:[1,0]
	v_pk_mul_f32 v[118:119], v[118:119], v[188:189] op_sel_hi:[1,0]
	v_pk_mul_f32 v[120:121], v[120:121], v[188:189] op_sel_hi:[1,0]
	v_pk_mul_f32 v[122:123], v[122:123], v[188:189] op_sel_hi:[1,0]
	v_pk_mul_f32 v[124:125], v[124:125], v[188:189] op_sel_hi:[1,0]
	v_pk_mul_f32 v[126:127], v[126:127], v[188:189] op_sel_hi:[1,0]
	v_pk_fma_f32 v[96:97], v[96:97], v[0:1], v[16:17]
	v_pk_fma_f32 v[98:99], v[98:99], v[2:3], v[18:19]
	v_pk_fma_f32 v[100:101], v[100:101], v[4:5], v[20:21]
	v_pk_fma_f32 v[102:103], v[102:103], v[6:7], v[22:23]
	v_pk_fma_f32 v[104:105], v[104:105], v[8:9], v[24:25]
	v_pk_fma_f32 v[106:107], v[106:107], v[10:11], v[26:27]
	v_pk_fma_f32 v[108:109], v[108:109], v[12:13], v[28:29]
	v_pk_fma_f32 v[110:111], v[110:111], v[14:15], v[30:31]
	v_pk_fma_f32 v[112:113], v[112:113], v[0:1], v[16:17]
	v_pk_fma_f32 v[114:115], v[114:115], v[2:3], v[18:19]
	v_pk_fma_f32 v[116:117], v[116:117], v[4:5], v[20:21]
	v_pk_fma_f32 v[118:119], v[118:119], v[6:7], v[22:23]
	v_pk_fma_f32 v[120:121], v[120:121], v[8:9], v[24:25]
	v_pk_fma_f32 v[122:123], v[122:123], v[10:11], v[26:27]
	v_pk_fma_f32 v[124:125], v[124:125], v[12:13], v[28:29]
	v_pk_fma_f32 v[126:127], v[126:127], v[14:15], v[30:31]
	v_cvt_pk_bf16_f32 v144, v96, v97
	v_cvt_pk_bf16_f32 v145, v98, v99
	v_cvt_pk_bf16_f32 v146, v100, v101
	v_cvt_pk_bf16_f32 v147, v102, v103
	v_cvt_pk_bf16_f32 v148, v104, v105
	v_cvt_pk_bf16_f32 v149, v106, v107
	v_cvt_pk_bf16_f32 v150, v108, v109
	v_cvt_pk_bf16_f32 v151, v110, v111
	v_cvt_pk_bf16_f32 v164, v112, v113
	v_cvt_pk_bf16_f32 v165, v114, v115
	v_cvt_pk_bf16_f32 v166, v116, v117
	v_cvt_pk_bf16_f32 v167, v118, v119
	v_cvt_pk_bf16_f32 v168, v120, v121
	v_cvt_pk_bf16_f32 v169, v122, v123
	v_cvt_pk_bf16_f32 v170, v124, v125
	v_cvt_pk_bf16_f32 v171, v126, v127
	s_add_u32 s18, s18, 0x1000
	s_addc_u32 s19, s19, 0
	global_store_dwordx4 v179, v[144:147], s[18:19] offset:-2048
	global_store_dwordx4 v179, v[148:151], s[18:19] offset:-1024
	global_store_dwordx4 v179, v[164:167], s[18:19] offset:0
	global_store_dwordx4 v179, v[168:171], s[18:19] offset:1024
	s_add_u32 s16, s16, 0x2000
	s_addc_u32 s17, s17, 0
	global_load_dwordx4 v[96:99], v178, s[16:17] offset:-4096 nt
	global_load_dwordx4 v[100:103], v178, s[16:17] offset:-4080 nt
	global_load_dwordx4 v[104:107], v178, s[16:17] offset:-2048 nt
	global_load_dwordx4 v[108:111], v178, s[16:17] offset:-2032 nt
	global_load_dwordx4 v[112:115], v178, s[16:17] offset:0 nt
	global_load_dwordx4 v[116:119], v178, s[16:17] offset:16 nt
	global_load_dwordx4 v[120:123], v178, s[16:17] offset:2048 nt
	global_load_dwordx4 v[124:127], v178, s[16:17] offset:2064 nt
	s_waitcnt vmcnt(24)
	v_pk_mul_f32 v[180:181], v[32:33], v[32:33]
	v_pk_mul_f32 v[182:183], v[48:49], v[48:49]
	v_pk_fma_f32 v[180:181], v[34:35], v[34:35], v[180:181]
	v_pk_fma_f32 v[182:183], v[50:51], v[50:51], v[182:183]
	v_pk_fma_f32 v[180:181], v[36:37], v[36:37], v[180:181]
	v_pk_fma_f32 v[182:183], v[52:53], v[52:53], v[182:183]
	v_pk_fma_f32 v[180:181], v[38:39], v[38:39], v[180:181]
	v_pk_fma_f32 v[182:183], v[54:55], v[54:55], v[182:183]
	v_pk_fma_f32 v[180:181], v[40:41], v[40:41], v[180:181]
	v_pk_fma_f32 v[182:183], v[56:57], v[56:57], v[182:183]
	v_pk_fma_f32 v[180:181], v[42:43], v[42:43], v[180:181]
	v_pk_fma_f32 v[182:183], v[58:59], v[58:59], v[182:183]
	v_pk_fma_f32 v[180:181], v[44:45], v[44:45], v[180:181]
	v_pk_fma_f32 v[182:183], v[60:61], v[60:61], v[182:183]
	v_pk_fma_f32 v[180:181], v[46:47], v[46:47], v[180:181]
	v_pk_fma_f32 v[182:183], v[62:63], v[62:63], v[182:183]
	v_add_f32_e32 v180, v180, v181
	v_add_f32_e32 v182, v182, v183
	ds_bpermute_b32 v184, v172, v180
	ds_bpermute_b32 v185, v172, v182
	s_waitcnt lgkmcnt(1)
	v_add_f32_e32 v180, v180, v184
	s_waitcnt lgkmcnt(0)
	v_add_f32_e32 v182, v182, v185
	ds_bpermute_b32 v184, v173, v180
	ds_bpermute_b32 v185, v173, v182
	s_waitcnt lgkmcnt(1)
	v_add_f32_e32 v180, v180, v184
	s_waitcnt lgkmcnt(0)
	v_add_f32_e32 v182, v182, v185
	ds_bpermute_b32 v184, v174, v180
	ds_bpermute_b32 v185, v174, v182
	s_waitcnt lgkmcnt(1)
	v_add_f32_e32 v180, v180, v184
	s_waitcnt lgkmcnt(0)
	v_add_f32_e32 v182, v182, v185
	ds_bpermute_b32 v184, v175, v180
	ds_bpermute_b32 v185, v175, v182
	s_waitcnt lgkmcnt(1)
	v_add_f32_e32 v180, v180, v184
	s_waitcnt lgkmcnt(0)
	v_add_f32_e32 v182, v182, v185
	ds_bpermute_b32 v184, v176, v180
	ds_bpermute_b32 v185, v176, v182
	s_waitcnt lgkmcnt(1)
	v_add_f32_e32 v180, v180, v184
	s_waitcnt lgkmcnt(0)
	v_add_f32_e32 v182, v182, v185
	ds_bpermute_b32 v184, v177, v180
	ds_bpermute_b32 v185, v177, v182
	s_waitcnt lgkmcnt(1)
	v_add_f32_e32 v180, v180, v184
	s_waitcnt lgkmcnt(0)
	v_add_f32_e32 v182, v182, v185
	v_mov_b32_e32 v184, 0x358637bd
	v_fmamk_f32 v180, v180, 0x3a800000, v184
	v_fmamk_f32 v182, v182, 0x3a800000, v184
	v_rsq_f32_e32 v186, v180
	v_rsq_f32_e32 v188, v182
	v_pk_mul_f32 v[32:33], v[32:33], v[186:187] op_sel_hi:[1,0]
	v_pk_mul_f32 v[34:35], v[34:35], v[186:187] op_sel_hi:[1,0]
	v_pk_mul_f32 v[36:37], v[36:37], v[186:187] op_sel_hi:[1,0]
	v_pk_mul_f32 v[38:39], v[38:39], v[186:187] op_sel_hi:[1,0]
	v_pk_mul_f32 v[40:41], v[40:41], v[186:187] op_sel_hi:[1,0]
	v_pk_mul_f32 v[42:43], v[42:43], v[186:187] op_sel_hi:[1,0]
	v_pk_mul_f32 v[44:45], v[44:45], v[186:187] op_sel_hi:[1,0]
	v_pk_mul_f32 v[46:47], v[46:47], v[186:187] op_sel_hi:[1,0]
	v_pk_mul_f32 v[48:49], v[48:49], v[188:189] op_sel_hi:[1,0]
	v_pk_mul_f32 v[50:51], v[50:51], v[188:189] op_sel_hi:[1,0]
	v_pk_mul_f32 v[52:53], v[52:53], v[188:189] op_sel_hi:[1,0]
	v_pk_mul_f32 v[54:55], v[54:55], v[188:189] op_sel_hi:[1,0]
	v_pk_mul_f32 v[56:57], v[56:57], v[188:189] op_sel_hi:[1,0]
	v_pk_mul_f32 v[58:59], v[58:59], v[188:189] op_sel_hi:[1,0]
	v_pk_mul_f32 v[60:61], v[60:61], v[188:189] op_sel_hi:[1,0]
	v_pk_mul_f32 v[62:63], v[62:63], v[188:189] op_sel_hi:[1,0]
	v_pk_fma_f32 v[32:33], v[32:33], v[0:1], v[16:17]
	v_pk_fma_f32 v[34:35], v[34:35], v[2:3], v[18:19]
	v_pk_fma_f32 v[36:37], v[36:37], v[4:5], v[20:21]
	v_pk_fma_f32 v[38:39], v[38:39], v[6:7], v[22:23]
	v_pk_fma_f32 v[40:41], v[40:41], v[8:9], v[24:25]
	v_pk_fma_f32 v[42:43], v[42:43], v[10:11], v[26:27]
	v_pk_fma_f32 v[44:45], v[44:45], v[12:13], v[28:29]
	v_pk_fma_f32 v[46:47], v[46:47], v[14:15], v[30:31]
	v_pk_fma_f32 v[48:49], v[48:49], v[0:1], v[16:17]
	v_pk_fma_f32 v[50:51], v[50:51], v[2:3], v[18:19]
	v_pk_fma_f32 v[52:53], v[52:53], v[4:5], v[20:21]
	v_pk_fma_f32 v[54:55], v[54:55], v[6:7], v[22:23]
	v_pk_fma_f32 v[56:57], v[56:57], v[8:9], v[24:25]
	v_pk_fma_f32 v[58:59], v[58:59], v[10:11], v[26:27]
	v_pk_fma_f32 v[60:61], v[60:61], v[12:13], v[28:29]
	v_pk_fma_f32 v[62:63], v[62:63], v[14:15], v[30:31]
	v_cvt_pk_bf16_f32 v144, v32, v33
	v_cvt_pk_bf16_f32 v145, v34, v35
	v_cvt_pk_bf16_f32 v146, v36, v37
	v_cvt_pk_bf16_f32 v147, v38, v39
	v_cvt_pk_bf16_f32 v148, v40, v41
	v_cvt_pk_bf16_f32 v149, v42, v43
	v_cvt_pk_bf16_f32 v150, v44, v45
	v_cvt_pk_bf16_f32 v151, v46, v47
	v_cvt_pk_bf16_f32 v164, v48, v49
	v_cvt_pk_bf16_f32 v165, v50, v51
	v_cvt_pk_bf16_f32 v166, v52, v53
	v_cvt_pk_bf16_f32 v167, v54, v55
	v_cvt_pk_bf16_f32 v168, v56, v57
	v_cvt_pk_bf16_f32 v169, v58, v59
	v_cvt_pk_bf16_f32 v170, v60, v61
	v_cvt_pk_bf16_f32 v171, v62, v63
	s_add_u32 s18, s18, 0x1000
	s_addc_u32 s19, s19, 0
	global_store_dwordx4 v179, v[144:147], s[18:19] offset:-2048
	global_store_dwordx4 v179, v[148:151], s[18:19] offset:-1024
	global_store_dwordx4 v179, v[164:167], s[18:19] offset:0
	global_store_dwordx4 v179, v[168:171], s[18:19] offset:1024
	s_add_u32 s16, s16, 0x2000
	s_addc_u32 s17, s17, 0
	global_load_dwordx4 v[32:35], v178, s[16:17] offset:-4096 nt
	global_load_dwordx4 v[36:39], v178, s[16:17] offset:-4080 nt
	global_load_dwordx4 v[40:43], v178, s[16:17] offset:-2048 nt
	global_load_dwordx4 v[44:47], v178, s[16:17] offset:-2032 nt
	global_load_dwordx4 v[48:51], v178, s[16:17] offset:0 nt
	global_load_dwordx4 v[52:55], v178, s[16:17] offset:16 nt
	global_load_dwordx4 v[56:59], v178, s[16:17] offset:2048 nt
	global_load_dwordx4 v[60:63], v178, s[16:17] offset:2064 nt
	s_waitcnt vmcnt(24)
	v_pk_mul_f32 v[180:181], v[64:65], v[64:65]
	v_pk_mul_f32 v[182:183], v[80:81], v[80:81]
	v_pk_fma_f32 v[180:181], v[66:67], v[66:67], v[180:181]
	v_pk_fma_f32 v[182:183], v[82:83], v[82:83], v[182:183]
	v_pk_fma_f32 v[180:181], v[68:69], v[68:69], v[180:181]
	v_pk_fma_f32 v[182:183], v[84:85], v[84:85], v[182:183]
	v_pk_fma_f32 v[180:181], v[70:71], v[70:71], v[180:181]
	v_pk_fma_f32 v[182:183], v[86:87], v[86:87], v[182:183]
	v_pk_fma_f32 v[180:181], v[72:73], v[72:73], v[180:181]
	v_pk_fma_f32 v[182:183], v[88:89], v[88:89], v[182:183]
	v_pk_fma_f32 v[180:181], v[74:75], v[74:75], v[180:181]
	v_pk_fma_f32 v[182:183], v[90:91], v[90:91], v[182:183]
	v_pk_fma_f32 v[180:181], v[76:77], v[76:77], v[180:181]
	v_pk_fma_f32 v[182:183], v[92:93], v[92:93], v[182:183]
	v_pk_fma_f32 v[180:181], v[78:79], v[78:79], v[180:181]
	v_pk_fma_f32 v[182:183], v[94:95], v[94:95], v[182:183]
	v_add_f32_e32 v180, v180, v181
	v_add_f32_e32 v182, v182, v183
	ds_bpermute_b32 v184, v172, v180
	ds_bpermute_b32 v185, v172, v182
	s_waitcnt lgkmcnt(1)
	v_add_f32_e32 v180, v180, v184
	s_waitcnt lgkmcnt(0)
	v_add_f32_e32 v182, v182, v185
	ds_bpermute_b32 v184, v173, v180
	ds_bpermute_b32 v185, v173, v182
	s_waitcnt lgkmcnt(1)
	v_add_f32_e32 v180, v180, v184
	s_waitcnt lgkmcnt(0)
	v_add_f32_e32 v182, v182, v185
	ds_bpermute_b32 v184, v174, v180
	ds_bpermute_b32 v185, v174, v182
	s_waitcnt lgkmcnt(1)
	v_add_f32_e32 v180, v180, v184
	s_waitcnt lgkmcnt(0)
	v_add_f32_e32 v182, v182, v185
	ds_bpermute_b32 v184, v175, v180
	ds_bpermute_b32 v185, v175, v182
	s_waitcnt lgkmcnt(1)
	v_add_f32_e32 v180, v180, v184
	s_waitcnt lgkmcnt(0)
	v_add_f32_e32 v182, v182, v185
	ds_bpermute_b32 v184, v176, v180
	ds_bpermute_b32 v185, v176, v182
	s_waitcnt lgkmcnt(1)
	v_add_f32_e32 v180, v180, v184
	s_waitcnt lgkmcnt(0)
	v_add_f32_e32 v182, v182, v185
	ds_bpermute_b32 v184, v177, v180
	ds_bpermute_b32 v185, v177, v182
	s_waitcnt lgkmcnt(1)
	v_add_f32_e32 v180, v180, v184
	s_waitcnt lgkmcnt(0)
	v_add_f32_e32 v182, v182, v185
	v_mov_b32_e32 v184, 0x358637bd
	v_fmamk_f32 v180, v180, 0x3a800000, v184
	v_fmamk_f32 v182, v182, 0x3a800000, v184
	v_rsq_f32_e32 v186, v180
	v_rsq_f32_e32 v188, v182
	v_pk_mul_f32 v[64:65], v[64:65], v[186:187] op_sel_hi:[1,0]
	v_pk_mul_f32 v[66:67], v[66:67], v[186:187] op_sel_hi:[1,0]
	v_pk_mul_f32 v[68:69], v[68:69], v[186:187] op_sel_hi:[1,0]
	v_pk_mul_f32 v[70:71], v[70:71], v[186:187] op_sel_hi:[1,0]
	v_pk_mul_f32 v[72:73], v[72:73], v[186:187] op_sel_hi:[1,0]
	v_pk_mul_f32 v[74:75], v[74:75], v[186:187] op_sel_hi:[1,0]
	v_pk_mul_f32 v[76:77], v[76:77], v[186:187] op_sel_hi:[1,0]
	v_pk_mul_f32 v[78:79], v[78:79], v[186:187] op_sel_hi:[1,0]
	v_pk_mul_f32 v[80:81], v[80:81], v[188:189] op_sel_hi:[1,0]
	v_pk_mul_f32 v[82:83], v[82:83], v[188:189] op_sel_hi:[1,0]
	v_pk_mul_f32 v[84:85], v[84:85], v[188:189] op_sel_hi:[1,0]
	v_pk_mul_f32 v[86:87], v[86:87], v[188:189] op_sel_hi:[1,0]
	v_pk_mul_f32 v[88:89], v[88:89], v[188:189] op_sel_hi:[1,0]
	v_pk_mul_f32 v[90:91], v[90:91], v[188:189] op_sel_hi:[1,0]
	v_pk_mul_f32 v[92:93], v[92:93], v[188:189] op_sel_hi:[1,0]
	v_pk_mul_f32 v[94:95], v[94:95], v[188:189] op_sel_hi:[1,0]
	v_pk_fma_f32 v[64:65], v[64:65], v[0:1], v[16:17]
	v_pk_fma_f32 v[66:67], v[66:67], v[2:3], v[18:19]
	v_pk_fma_f32 v[68:69], v[68:69], v[4:5], v[20:21]
	v_pk_fma_f32 v[70:71], v[70:71], v[6:7], v[22:23]
	v_pk_fma_f32 v[72:73], v[72:73], v[8:9], v[24:25]
	v_pk_fma_f32 v[74:75], v[74:75], v[10:11], v[26:27]
	v_pk_fma_f32 v[76:77], v[76:77], v[12:13], v[28:29]
	v_pk_fma_f32 v[78:79], v[78:79], v[14:15], v[30:31]
	v_pk_fma_f32 v[80:81], v[80:81], v[0:1], v[16:17]
	v_pk_fma_f32 v[82:83], v[82:83], v[2:3], v[18:19]
	v_pk_fma_f32 v[84:85], v[84:85], v[4:5], v[20:21]
	v_pk_fma_f32 v[86:87], v[86:87], v[6:7], v[22:23]
	v_pk_fma_f32 v[88:89], v[88:89], v[8:9], v[24:25]
	v_pk_fma_f32 v[90:91], v[90:91], v[10:11], v[26:27]
	v_pk_fma_f32 v[92:93], v[92:93], v[12:13], v[28:29]
	v_pk_fma_f32 v[94:95], v[94:95], v[14:15], v[30:31]
	v_cvt_pk_bf16_f32 v144, v64, v65
	v_cvt_pk_bf16_f32 v145, v66, v67
	v_cvt_pk_bf16_f32 v146, v68, v69
	v_cvt_pk_bf16_f32 v147, v70, v71
	v_cvt_pk_bf16_f32 v148, v72, v73
	v_cvt_pk_bf16_f32 v149, v74, v75
	v_cvt_pk_bf16_f32 v150, v76, v77
	v_cvt_pk_bf16_f32 v151, v78, v79
	v_cvt_pk_bf16_f32 v164, v80, v81
	v_cvt_pk_bf16_f32 v165, v82, v83
	v_cvt_pk_bf16_f32 v166, v84, v85
	v_cvt_pk_bf16_f32 v167, v86, v87
	v_cvt_pk_bf16_f32 v168, v88, v89
	v_cvt_pk_bf16_f32 v169, v90, v91
	v_cvt_pk_bf16_f32 v170, v92, v93
	v_cvt_pk_bf16_f32 v171, v94, v95
	s_add_u32 s18, s18, 0x1000
	s_addc_u32 s19, s19, 0
	global_store_dwordx4 v179, v[144:147], s[18:19] offset:-2048
	global_store_dwordx4 v179, v[148:151], s[18:19] offset:-1024
	global_store_dwordx4 v179, v[164:167], s[18:19] offset:0
	global_store_dwordx4 v179, v[168:171], s[18:19] offset:1024
	s_add_u32 s16, s16, 0x2000
	s_addc_u32 s17, s17, 0
	global_load_dwordx4 v[64:67], v178, s[16:17] offset:-4096 nt
	global_load_dwordx4 v[68:71], v178, s[16:17] offset:-4080 nt
	global_load_dwordx4 v[72:75], v178, s[16:17] offset:-2048 nt
	global_load_dwordx4 v[76:79], v178, s[16:17] offset:-2032 nt
	global_load_dwordx4 v[80:83], v178, s[16:17] offset:0 nt
	global_load_dwordx4 v[84:87], v178, s[16:17] offset:16 nt
	global_load_dwordx4 v[88:91], v178, s[16:17] offset:2048 nt
	global_load_dwordx4 v[92:95], v178, s[16:17] offset:2064 nt
	s_waitcnt vmcnt(24)
	v_pk_mul_f32 v[180:181], v[96:97], v[96:97]
	v_pk_mul_f32 v[182:183], v[112:113], v[112:113]
	v_pk_fma_f32 v[180:181], v[98:99], v[98:99], v[180:181]
	v_pk_fma_f32 v[182:183], v[114:115], v[114:115], v[182:183]
	v_pk_fma_f32 v[180:181], v[100:101], v[100:101], v[180:181]
	v_pk_fma_f32 v[182:183], v[116:117], v[116:117], v[182:183]
	v_pk_fma_f32 v[180:181], v[102:103], v[102:103], v[180:181]
	v_pk_fma_f32 v[182:183], v[118:119], v[118:119], v[182:183]
	v_pk_fma_f32 v[180:181], v[104:105], v[104:105], v[180:181]
	v_pk_fma_f32 v[182:183], v[120:121], v[120:121], v[182:183]
	v_pk_fma_f32 v[180:181], v[106:107], v[106:107], v[180:181]
	v_pk_fma_f32 v[182:183], v[122:123], v[122:123], v[182:183]
	v_pk_fma_f32 v[180:181], v[108:109], v[108:109], v[180:181]
	v_pk_fma_f32 v[182:183], v[124:125], v[124:125], v[182:183]
	v_pk_fma_f32 v[180:181], v[110:111], v[110:111], v[180:181]
	v_pk_fma_f32 v[182:183], v[126:127], v[126:127], v[182:183]
	v_add_f32_e32 v180, v180, v181
	v_add_f32_e32 v182, v182, v183
	ds_bpermute_b32 v184, v172, v180
	ds_bpermute_b32 v185, v172, v182
	s_waitcnt lgkmcnt(1)
	v_add_f32_e32 v180, v180, v184
	s_waitcnt lgkmcnt(0)
	v_add_f32_e32 v182, v182, v185
	ds_bpermute_b32 v184, v173, v180
	ds_bpermute_b32 v185, v173, v182
	s_waitcnt lgkmcnt(1)
	v_add_f32_e32 v180, v180, v184
	s_waitcnt lgkmcnt(0)
	v_add_f32_e32 v182, v182, v185
	ds_bpermute_b32 v184, v174, v180
	ds_bpermute_b32 v185, v174, v182
	s_waitcnt lgkmcnt(1)
	v_add_f32_e32 v180, v180, v184
	s_waitcnt lgkmcnt(0)
	v_add_f32_e32 v182, v182, v185
	ds_bpermute_b32 v184, v175, v180
	ds_bpermute_b32 v185, v175, v182
	s_waitcnt lgkmcnt(1)
	v_add_f32_e32 v180, v180, v184
	s_waitcnt lgkmcnt(0)
	v_add_f32_e32 v182, v182, v185
	ds_bpermute_b32 v184, v176, v180
	ds_bpermute_b32 v185, v176, v182
	s_waitcnt lgkmcnt(1)
	v_add_f32_e32 v180, v180, v184
	s_waitcnt lgkmcnt(0)
	v_add_f32_e32 v182, v182, v185
	ds_bpermute_b32 v184, v177, v180
	ds_bpermute_b32 v185, v177, v182
	s_waitcnt lgkmcnt(1)
	v_add_f32_e32 v180, v180, v184
	s_waitcnt lgkmcnt(0)
	v_add_f32_e32 v182, v182, v185
	v_mov_b32_e32 v184, 0x358637bd
	v_fmamk_f32 v180, v180, 0x3a800000, v184
	v_fmamk_f32 v182, v182, 0x3a800000, v184
	v_rsq_f32_e32 v186, v180
	v_rsq_f32_e32 v188, v182
	v_pk_mul_f32 v[96:97], v[96:97], v[186:187] op_sel_hi:[1,0]
	v_pk_mul_f32 v[98:99], v[98:99], v[186:187] op_sel_hi:[1,0]
	v_pk_mul_f32 v[100:101], v[100:101], v[186:187] op_sel_hi:[1,0]
	v_pk_mul_f32 v[102:103], v[102:103], v[186:187] op_sel_hi:[1,0]
	v_pk_mul_f32 v[104:105], v[104:105], v[186:187] op_sel_hi:[1,0]
	v_pk_mul_f32 v[106:107], v[106:107], v[186:187] op_sel_hi:[1,0]
	v_pk_mul_f32 v[108:109], v[108:109], v[186:187] op_sel_hi:[1,0]
	v_pk_mul_f32 v[110:111], v[110:111], v[186:187] op_sel_hi:[1,0]
	v_pk_mul_f32 v[112:113], v[112:113], v[188:189] op_sel_hi:[1,0]
	v_pk_mul_f32 v[114:115], v[114:115], v[188:189] op_sel_hi:[1,0]
	v_pk_mul_f32 v[116:117], v[116:117], v[188:189] op_sel_hi:[1,0]
	v_pk_mul_f32 v[118:119], v[118:119], v[188:189] op_sel_hi:[1,0]
	v_pk_mul_f32 v[120:121], v[120:121], v[188:189] op_sel_hi:[1,0]
	v_pk_mul_f32 v[122:123], v[122:123], v[188:189] op_sel_hi:[1,0]
	v_pk_mul_f32 v[124:125], v[124:125], v[188:189] op_sel_hi:[1,0]
	v_pk_mul_f32 v[126:127], v[126:127], v[188:189] op_sel_hi:[1,0]
	v_pk_fma_f32 v[96:97], v[96:97], v[0:1], v[16:17]
	v_pk_fma_f32 v[98:99], v[98:99], v[2:3], v[18:19]
	v_pk_fma_f32 v[100:101], v[100:101], v[4:5], v[20:21]
	v_pk_fma_f32 v[102:103], v[102:103], v[6:7], v[22:23]
	v_pk_fma_f32 v[104:105], v[104:105], v[8:9], v[24:25]
	v_pk_fma_f32 v[106:107], v[106:107], v[10:11], v[26:27]
	v_pk_fma_f32 v[108:109], v[108:109], v[12:13], v[28:29]
	v_pk_fma_f32 v[110:111], v[110:111], v[14:15], v[30:31]
	v_pk_fma_f32 v[112:113], v[112:113], v[0:1], v[16:17]
	v_pk_fma_f32 v[114:115], v[114:115], v[2:3], v[18:19]
	v_pk_fma_f32 v[116:117], v[116:117], v[4:5], v[20:21]
	v_pk_fma_f32 v[118:119], v[118:119], v[6:7], v[22:23]
	v_pk_fma_f32 v[120:121], v[120:121], v[8:9], v[24:25]
	v_pk_fma_f32 v[122:123], v[122:123], v[10:11], v[26:27]
	v_pk_fma_f32 v[124:125], v[124:125], v[12:13], v[28:29]
	v_pk_fma_f32 v[126:127], v[126:127], v[14:15], v[30:31]
	v_cvt_pk_bf16_f32 v144, v96, v97
	v_cvt_pk_bf16_f32 v145, v98, v99
	v_cvt_pk_bf16_f32 v146, v100, v101
	v_cvt_pk_bf16_f32 v147, v102, v103
	v_cvt_pk_bf16_f32 v148, v104, v105
	v_cvt_pk_bf16_f32 v149, v106, v107
	v_cvt_pk_bf16_f32 v150, v108, v109
	v_cvt_pk_bf16_f32 v151, v110, v111
	v_cvt_pk_bf16_f32 v164, v112, v113
	v_cvt_pk_bf16_f32 v165, v114, v115
	v_cvt_pk_bf16_f32 v166, v116, v117
	v_cvt_pk_bf16_f32 v167, v118, v119
	v_cvt_pk_bf16_f32 v168, v120, v121
	v_cvt_pk_bf16_f32 v169, v122, v123
	v_cvt_pk_bf16_f32 v170, v124, v125
	v_cvt_pk_bf16_f32 v171, v126, v127
	s_add_u32 s18, s18, 0x1000
	s_addc_u32 s19, s19, 0
	global_store_dwordx4 v179, v[144:147], s[18:19] offset:-2048
	global_store_dwordx4 v179, v[148:151], s[18:19] offset:-1024
	global_store_dwordx4 v179, v[164:167], s[18:19] offset:0
	global_store_dwordx4 v179, v[168:171], s[18:19] offset:1024
	s_waitcnt vmcnt(16)
	v_pk_mul_f32 v[180:181], v[32:33], v[32:33]
	v_pk_mul_f32 v[182:183], v[48:49], v[48:49]
	v_pk_fma_f32 v[180:181], v[34:35], v[34:35], v[180:181]
	v_pk_fma_f32 v[182:183], v[50:51], v[50:51], v[182:183]
	v_pk_fma_f32 v[180:181], v[36:37], v[36:37], v[180:181]
	v_pk_fma_f32 v[182:183], v[52:53], v[52:53], v[182:183]
	v_pk_fma_f32 v[180:181], v[38:39], v[38:39], v[180:181]
	v_pk_fma_f32 v[182:183], v[54:55], v[54:55], v[182:183]
	v_pk_fma_f32 v[180:181], v[40:41], v[40:41], v[180:181]
	v_pk_fma_f32 v[182:183], v[56:57], v[56:57], v[182:183]
	v_pk_fma_f32 v[180:181], v[42:43], v[42:43], v[180:181]
	v_pk_fma_f32 v[182:183], v[58:59], v[58:59], v[182:183]
	v_pk_fma_f32 v[180:181], v[44:45], v[44:45], v[180:181]
	v_pk_fma_f32 v[182:183], v[60:61], v[60:61], v[182:183]
	v_pk_fma_f32 v[180:181], v[46:47], v[46:47], v[180:181]
	v_pk_fma_f32 v[182:183], v[62:63], v[62:63], v[182:183]
	v_add_f32_e32 v180, v180, v181
	v_add_f32_e32 v182, v182, v183
	ds_bpermute_b32 v184, v172, v180
	ds_bpermute_b32 v185, v172, v182
	s_waitcnt lgkmcnt(1)
	v_add_f32_e32 v180, v180, v184
	s_waitcnt lgkmcnt(0)
	v_add_f32_e32 v182, v182, v185
	ds_bpermute_b32 v184, v173, v180
	ds_bpermute_b32 v185, v173, v182
	s_waitcnt lgkmcnt(1)
	v_add_f32_e32 v180, v180, v184
	s_waitcnt lgkmcnt(0)
	v_add_f32_e32 v182, v182, v185
	ds_bpermute_b32 v184, v174, v180
	ds_bpermute_b32 v185, v174, v182
	s_waitcnt lgkmcnt(1)
	v_add_f32_e32 v180, v180, v184
	s_waitcnt lgkmcnt(0)
	v_add_f32_e32 v182, v182, v185
	ds_bpermute_b32 v184, v175, v180
	ds_bpermute_b32 v185, v175, v182
	s_waitcnt lgkmcnt(1)
	v_add_f32_e32 v180, v180, v184
	s_waitcnt lgkmcnt(0)
	v_add_f32_e32 v182, v182, v185
	ds_bpermute_b32 v184, v176, v180
	ds_bpermute_b32 v185, v176, v182
	s_waitcnt lgkmcnt(1)
	v_add_f32_e32 v180, v180, v184
	s_waitcnt lgkmcnt(0)
	v_add_f32_e32 v182, v182, v185
	ds_bpermute_b32 v184, v177, v180
	ds_bpermute_b32 v185, v177, v182
	s_waitcnt lgkmcnt(1)
	v_add_f32_e32 v180, v180, v184
	s_waitcnt lgkmcnt(0)
	v_add_f32_e32 v182, v182, v185
	v_mov_b32_e32 v184, 0x358637bd
	v_fmamk_f32 v180, v180, 0x3a800000, v184
	v_fmamk_f32 v182, v182, 0x3a800000, v184
	v_rsq_f32_e32 v186, v180
	v_rsq_f32_e32 v188, v182
	v_pk_mul_f32 v[32:33], v[32:33], v[186:187] op_sel_hi:[1,0]
	v_pk_mul_f32 v[34:35], v[34:35], v[186:187] op_sel_hi:[1,0]
	v_pk_mul_f32 v[36:37], v[36:37], v[186:187] op_sel_hi:[1,0]
	v_pk_mul_f32 v[38:39], v[38:39], v[186:187] op_sel_hi:[1,0]
	v_pk_mul_f32 v[40:41], v[40:41], v[186:187] op_sel_hi:[1,0]
	v_pk_mul_f32 v[42:43], v[42:43], v[186:187] op_sel_hi:[1,0]
	v_pk_mul_f32 v[44:45], v[44:45], v[186:187] op_sel_hi:[1,0]
	v_pk_mul_f32 v[46:47], v[46:47], v[186:187] op_sel_hi:[1,0]
	v_pk_mul_f32 v[48:49], v[48:49], v[188:189] op_sel_hi:[1,0]
	v_pk_mul_f32 v[50:51], v[50:51], v[188:189] op_sel_hi:[1,0]
	v_pk_mul_f32 v[52:53], v[52:53], v[188:189] op_sel_hi:[1,0]
	v_pk_mul_f32 v[54:55], v[54:55], v[188:189] op_sel_hi:[1,0]
	v_pk_mul_f32 v[56:57], v[56:57], v[188:189] op_sel_hi:[1,0]
	v_pk_mul_f32 v[58:59], v[58:59], v[188:189] op_sel_hi:[1,0]
	v_pk_mul_f32 v[60:61], v[60:61], v[188:189] op_sel_hi:[1,0]
	v_pk_mul_f32 v[62:63], v[62:63], v[188:189] op_sel_hi:[1,0]
	v_pk_fma_f32 v[32:33], v[32:33], v[0:1], v[16:17]
	v_pk_fma_f32 v[34:35], v[34:35], v[2:3], v[18:19]
	v_pk_fma_f32 v[36:37], v[36:37], v[4:5], v[20:21]
	v_pk_fma_f32 v[38:39], v[38:39], v[6:7], v[22:23]
	v_pk_fma_f32 v[40:41], v[40:41], v[8:9], v[24:25]
	v_pk_fma_f32 v[42:43], v[42:43], v[10:11], v[26:27]
	v_pk_fma_f32 v[44:45], v[44:45], v[12:13], v[28:29]
	v_pk_fma_f32 v[46:47], v[46:47], v[14:15], v[30:31]
	v_pk_fma_f32 v[48:49], v[48:49], v[0:1], v[16:17]
	v_pk_fma_f32 v[50:51], v[50:51], v[2:3], v[18:19]
	v_pk_fma_f32 v[52:53], v[52:53], v[4:5], v[20:21]
	v_pk_fma_f32 v[54:55], v[54:55], v[6:7], v[22:23]
	v_pk_fma_f32 v[56:57], v[56:57], v[8:9], v[24:25]
	v_pk_fma_f32 v[58:59], v[58:59], v[10:11], v[26:27]
	v_pk_fma_f32 v[60:61], v[60:61], v[12:13], v[28:29]
	v_pk_fma_f32 v[62:63], v[62:63], v[14:15], v[30:31]
	v_cvt_pk_bf16_f32 v144, v32, v33
	v_cvt_pk_bf16_f32 v145, v34, v35
	v_cvt_pk_bf16_f32 v146, v36, v37
	v_cvt_pk_bf16_f32 v147, v38, v39
	v_cvt_pk_bf16_f32 v148, v40, v41
	v_cvt_pk_bf16_f32 v149, v42, v43
	v_cvt_pk_bf16_f32 v150, v44, v45
	v_cvt_pk_bf16_f32 v151, v46, v47
	v_cvt_pk_bf16_f32 v164, v48, v49
	v_cvt_pk_bf16_f32 v165, v50, v51
	v_cvt_pk_bf16_f32 v166, v52, v53
	v_cvt_pk_bf16_f32 v167, v54, v55
	v_cvt_pk_bf16_f32 v168, v56, v57
	v_cvt_pk_bf16_f32 v169, v58, v59
	v_cvt_pk_bf16_f32 v170, v60, v61
	v_cvt_pk_bf16_f32 v171, v62, v63
	s_add_u32 s18, s18, 0x1000
	s_addc_u32 s19, s19, 0
	global_store_dwordx4 v179, v[144:147], s[18:19] offset:-2048
	global_store_dwordx4 v179, v[148:151], s[18:19] offset:-1024
	global_store_dwordx4 v179, v[164:167], s[18:19] offset:0
	global_store_dwordx4 v179, v[168:171], s[18:19] offset:1024
	s_waitcnt vmcnt(8)
	v_pk_mul_f32 v[180:181], v[64:65], v[64:65]
	v_pk_mul_f32 v[182:183], v[80:81], v[80:81]
	v_pk_fma_f32 v[180:181], v[66:67], v[66:67], v[180:181]
	v_pk_fma_f32 v[182:183], v[82:83], v[82:83], v[182:183]
	v_pk_fma_f32 v[180:181], v[68:69], v[68:69], v[180:181]
	v_pk_fma_f32 v[182:183], v[84:85], v[84:85], v[182:183]
	v_pk_fma_f32 v[180:181], v[70:71], v[70:71], v[180:181]
	v_pk_fma_f32 v[182:183], v[86:87], v[86:87], v[182:183]
	v_pk_fma_f32 v[180:181], v[72:73], v[72:73], v[180:181]
	v_pk_fma_f32 v[182:183], v[88:89], v[88:89], v[182:183]
	v_pk_fma_f32 v[180:181], v[74:75], v[74:75], v[180:181]
	v_pk_fma_f32 v[182:183], v[90:91], v[90:91], v[182:183]
	v_pk_fma_f32 v[180:181], v[76:77], v[76:77], v[180:181]
	v_pk_fma_f32 v[182:183], v[92:93], v[92:93], v[182:183]
	v_pk_fma_f32 v[180:181], v[78:79], v[78:79], v[180:181]
	v_pk_fma_f32 v[182:183], v[94:95], v[94:95], v[182:183]
	v_add_f32_e32 v180, v180, v181
	v_add_f32_e32 v182, v182, v183
	ds_bpermute_b32 v184, v172, v180
	ds_bpermute_b32 v185, v172, v182
	s_waitcnt lgkmcnt(1)
	v_add_f32_e32 v180, v180, v184
	s_waitcnt lgkmcnt(0)
	v_add_f32_e32 v182, v182, v185
	ds_bpermute_b32 v184, v173, v180
	ds_bpermute_b32 v185, v173, v182
	s_waitcnt lgkmcnt(1)
	v_add_f32_e32 v180, v180, v184
	s_waitcnt lgkmcnt(0)
	v_add_f32_e32 v182, v182, v185
	ds_bpermute_b32 v184, v174, v180
	ds_bpermute_b32 v185, v174, v182
	s_waitcnt lgkmcnt(1)
	v_add_f32_e32 v180, v180, v184
	s_waitcnt lgkmcnt(0)
	v_add_f32_e32 v182, v182, v185
	ds_bpermute_b32 v184, v175, v180
	ds_bpermute_b32 v185, v175, v182
	s_waitcnt lgkmcnt(1)
	v_add_f32_e32 v180, v180, v184
	s_waitcnt lgkmcnt(0)
	v_add_f32_e32 v182, v182, v185
	ds_bpermute_b32 v184, v176, v180
	ds_bpermute_b32 v185, v176, v182
	s_waitcnt lgkmcnt(1)
	v_add_f32_e32 v180, v180, v184
	s_waitcnt lgkmcnt(0)
	v_add_f32_e32 v182, v182, v185
	ds_bpermute_b32 v184, v177, v180
	ds_bpermute_b32 v185, v177, v182
	s_waitcnt lgkmcnt(1)
	v_add_f32_e32 v180, v180, v184
	s_waitcnt lgkmcnt(0)
	v_add_f32_e32 v182, v182, v185
	v_mov_b32_e32 v184, 0x358637bd
	v_fmamk_f32 v180, v180, 0x3a800000, v184
	v_fmamk_f32 v182, v182, 0x3a800000, v184
	v_rsq_f32_e32 v186, v180
	v_rsq_f32_e32 v188, v182
	v_pk_mul_f32 v[64:65], v[64:65], v[186:187] op_sel_hi:[1,0]
	v_pk_mul_f32 v[66:67], v[66:67], v[186:187] op_sel_hi:[1,0]
	v_pk_mul_f32 v[68:69], v[68:69], v[186:187] op_sel_hi:[1,0]
	v_pk_mul_f32 v[70:71], v[70:71], v[186:187] op_sel_hi:[1,0]
	v_pk_mul_f32 v[72:73], v[72:73], v[186:187] op_sel_hi:[1,0]
	v_pk_mul_f32 v[74:75], v[74:75], v[186:187] op_sel_hi:[1,0]
	v_pk_mul_f32 v[76:77], v[76:77], v[186:187] op_sel_hi:[1,0]
	v_pk_mul_f32 v[78:79], v[78:79], v[186:187] op_sel_hi:[1,0]
	v_pk_mul_f32 v[80:81], v[80:81], v[188:189] op_sel_hi:[1,0]
	v_pk_mul_f32 v[82:83], v[82:83], v[188:189] op_sel_hi:[1,0]
	v_pk_mul_f32 v[84:85], v[84:85], v[188:189] op_sel_hi:[1,0]
	v_pk_mul_f32 v[86:87], v[86:87], v[188:189] op_sel_hi:[1,0]
	v_pk_mul_f32 v[88:89], v[88:89], v[188:189] op_sel_hi:[1,0]
	v_pk_mul_f32 v[90:91], v[90:91], v[188:189] op_sel_hi:[1,0]
	v_pk_mul_f32 v[92:93], v[92:93], v[188:189] op_sel_hi:[1,0]
	v_pk_mul_f32 v[94:95], v[94:95], v[188:189] op_sel_hi:[1,0]
	v_pk_fma_f32 v[64:65], v[64:65], v[0:1], v[16:17]
	v_pk_fma_f32 v[66:67], v[66:67], v[2:3], v[18:19]
	v_pk_fma_f32 v[68:69], v[68:69], v[4:5], v[20:21]
	v_pk_fma_f32 v[70:71], v[70:71], v[6:7], v[22:23]
	v_pk_fma_f32 v[72:73], v[72:73], v[8:9], v[24:25]
	v_pk_fma_f32 v[74:75], v[74:75], v[10:11], v[26:27]
	v_pk_fma_f32 v[76:77], v[76:77], v[12:13], v[28:29]
	v_pk_fma_f32 v[78:79], v[78:79], v[14:15], v[30:31]
	v_pk_fma_f32 v[80:81], v[80:81], v[0:1], v[16:17]
	v_pk_fma_f32 v[82:83], v[82:83], v[2:3], v[18:19]
	v_pk_fma_f32 v[84:85], v[84:85], v[4:5], v[20:21]
	v_pk_fma_f32 v[86:87], v[86:87], v[6:7], v[22:23]
	v_pk_fma_f32 v[88:89], v[88:89], v[8:9], v[24:25]
	v_pk_fma_f32 v[90:91], v[90:91], v[10:11], v[26:27]
	v_pk_fma_f32 v[92:93], v[92:93], v[12:13], v[28:29]
	v_pk_fma_f32 v[94:95], v[94:95], v[14:15], v[30:31]
	v_cvt_pk_bf16_f32 v144, v64, v65
	v_cvt_pk_bf16_f32 v145, v66, v67
	v_cvt_pk_bf16_f32 v146, v68, v69
	v_cvt_pk_bf16_f32 v147, v70, v71
	v_cvt_pk_bf16_f32 v148, v72, v73
	v_cvt_pk_bf16_f32 v149, v74, v75
	v_cvt_pk_bf16_f32 v150, v76, v77
	v_cvt_pk_bf16_f32 v151, v78, v79
	v_cvt_pk_bf16_f32 v164, v80, v81
	v_cvt_pk_bf16_f32 v165, v82, v83
	v_cvt_pk_bf16_f32 v166, v84, v85
	v_cvt_pk_bf16_f32 v167, v86, v87
	v_cvt_pk_bf16_f32 v168, v88, v89
	v_cvt_pk_bf16_f32 v169, v90, v91
	v_cvt_pk_bf16_f32 v170, v92, v93
	v_cvt_pk_bf16_f32 v171, v94, v95
	s_add_u32 s18, s18, 0x1000
	s_addc_u32 s19, s19, 0
	global_store_dwordx4 v179, v[144:147], s[18:19] offset:-2048
	global_store_dwordx4 v179, v[148:151], s[18:19] offset:-1024
	global_store_dwordx4 v179, v[164:167], s[18:19] offset:0
	global_store_dwordx4 v179, v[168:171], s[18:19] offset:1024
	s_add_u32 s25, s25, s14
	s_cmp_lt_u32 s25, 0x800
	s_cbranch_scc1 .Lp1_group

.Lp1_cpair:
	s_add_u32 s20, s4, 0x18000
	s_addc_u32 s21, s5, 0
	s_add_u32 s22, s20, 0x1000
	s_addc_u32 s23, s21, 0
	global_load_dwordx4 v[0:3], v178, s[12:13] offset:0
	global_load_dwordx4 v[16:19], v178, s[20:21] offset:0
	global_load_dwordx4 v[128:131], v178, s[22:23] offset:0
	global_load_dwordx4 v[4:7], v178, s[12:13] offset:16
	global_load_dwordx4 v[20:23], v178, s[20:21] offset:16
	global_load_dwordx4 v[132:135], v178, s[22:23] offset:16
	global_load_dwordx4 v[8:11], v178, s[12:13] offset:2048
	global_load_dwordx4 v[24:27], v178, s[20:21] offset:2048
	global_load_dwordx4 v[136:139], v178, s[22:23] offset:2048
	global_load_dwordx4 v[12:15], v178, s[12:13] offset:2064
	global_load_dwordx4 v[28:31], v178, s[20:21] offset:2064
	global_load_dwordx4 v[140:143], v178, s[22:23] offset:2064
	s_lshl_b32 s24, s10, 13
	s_add_u32 s16, s8, s24
	s_addc_u32 s17, s9, 0
	s_add_u32 s16, s16, 0x1000
	s_addc_u32 s17, s17, 0
	s_lshl_b32 s24, s10, 12
	s_add_u32 s24, s24, 0x1C000800
	s_add_u32 s18, s4, s24
	s_addc_u32 s19, s5, 0
	global_load_dwordx4 v[32:35], v178, s[16:17] offset:-4096 nt
	global_load_dwordx4 v[36:39], v178, s[16:17] offset:-4080 nt
	global_load_dwordx4 v[40:43], v178, s[16:17] offset:-2048 nt
	global_load_dwordx4 v[44:47], v178, s[16:17] offset:-2032 nt
	global_load_dwordx4 v[48:51], v178, s[16:17] offset:0 nt
	global_load_dwordx4 v[52:55], v178, s[16:17] offset:16 nt
	global_load_dwordx4 v[56:59], v178, s[16:17] offset:2048 nt
	global_load_dwordx4 v[60:63], v178, s[16:17] offset:2064 nt
	s_waitcnt vmcnt(8)
	v_add_f32_e32 v128, 1.0, v128
	v_add_f32_e32 v129, 1.0, v129
	v_add_f32_e32 v130, 1.0, v130
	v_add_f32_e32 v131, 1.0, v131
	v_add_f32_e32 v132, 1.0, v132
	v_add_f32_e32 v133, 1.0, v133
	v_add_f32_e32 v134, 1.0, v134
	v_add_f32_e32 v135, 1.0, v135
	v_add_f32_e32 v136, 1.0, v136
	v_add_f32_e32 v137, 1.0, v137
	v_add_f32_e32 v138, 1.0, v138
	v_add_f32_e32 v139, 1.0, v139
	v_add_f32_e32 v140, 1.0, v140
	v_add_f32_e32 v141, 1.0, v141
	v_add_f32_e32 v142, 1.0, v142
	v_add_f32_e32 v143, 1.0, v143
	v_mul_f32_e32 v0, v0, v128
	v_mul_f32_e32 v1, v1, v129
	v_mul_f32_e32 v2, v2, v130
	v_mul_f32_e32 v3, v3, v131
	v_mul_f32_e32 v4, v4, v132
	v_mul_f32_e32 v5, v5, v133
	v_mul_f32_e32 v6, v6, v134
	v_mul_f32_e32 v7, v7, v135
	v_mul_f32_e32 v8, v8, v136
	v_mul_f32_e32 v9, v9, v137
	v_mul_f32_e32 v10, v10, v138
	v_mul_f32_e32 v11, v11, v139
	v_mul_f32_e32 v12, v12, v140
	v_mul_f32_e32 v13, v13, v141
	v_mul_f32_e32 v14, v14, v142
	v_mul_f32_e32 v15, v15, v143
	s_waitcnt vmcnt(0)
	v_pk_mul_f32 v[180:181], v[32:33], v[32:33]
	v_pk_mul_f32 v[182:183], v[48:49], v[48:49]
	v_pk_fma_f32 v[180:181], v[34:35], v[34:35], v[180:181]
	v_pk_fma_f32 v[182:183], v[50:51], v[50:51], v[182:183]
	v_pk_fma_f32 v[180:181], v[36:37], v[36:37], v[180:181]
	v_pk_fma_f32 v[182:183], v[52:53], v[52:53], v[182:183]
	v_pk_fma_f32 v[180:181], v[38:39], v[38:39], v[180:181]
	v_pk_fma_f32 v[182:183], v[54:55], v[54:55], v[182:183]
	v_pk_fma_f32 v[180:181], v[40:41], v[40:41], v[180:181]
	v_pk_fma_f32 v[182:183], v[56:57], v[56:57], v[182:183]
	v_pk_fma_f32 v[180:181], v[42:43], v[42:43], v[180:181]
	v_pk_fma_f32 v[182:183], v[58:59], v[58:59], v[182:183]
	v_pk_fma_f32 v[180:181], v[44:45], v[44:45], v[180:181]
	v_pk_fma_f32 v[182:183], v[60:61], v[60:61], v[182:183]
	v_pk_fma_f32 v[180:181], v[46:47], v[46:47], v[180:181]
	v_pk_fma_f32 v[182:183], v[62:63], v[62:63], v[182:183]
	v_add_f32_e32 v180, v180, v181
	v_add_f32_e32 v182, v182, v183
	ds_bpermute_b32 v184, v172, v180
	ds_bpermute_b32 v185, v172, v182
	s_waitcnt lgkmcnt(1)
	v_add_f32_e32 v180, v180, v184
	s_waitcnt lgkmcnt(0)
	v_add_f32_e32 v182, v182, v185
	ds_bpermute_b32 v184, v173, v180
	ds_bpermute_b32 v185, v173, v182
	s_waitcnt lgkmcnt(1)
	v_add_f32_e32 v180, v180, v184
	s_waitcnt lgkmcnt(0)
	v_add_f32_e32 v182, v182, v185
	ds_bpermute_b32 v184, v174, v180
	ds_bpermute_b32 v185, v174, v182
	s_waitcnt lgkmcnt(1)
	v_add_f32_e32 v180, v180, v184
	s_waitcnt lgkmcnt(0)
	v_add_f32_e32 v182, v182, v185
	ds_bpermute_b32 v184, v175, v180
	ds_bpermute_b32 v185, v175, v182
	s_waitcnt lgkmcnt(1)
	v_add_f32_e32 v180, v180, v184
	s_waitcnt lgkmcnt(0)
	v_add_f32_e32 v182, v182, v185
	ds_bpermute_b32 v184, v176, v180
	ds_bpermute_b32 v185, v176, v182
	s_waitcnt lgkmcnt(1)
	v_add_f32_e32 v180, v180, v184
	s_waitcnt lgkmcnt(0)
	v_add_f32_e32 v182, v182, v185
	ds_bpermute_b32 v184, v177, v180
	ds_bpermute_b32 v185, v177, v182
	s_waitcnt lgkmcnt(1)
	v_add_f32_e32 v180, v180, v184
	s_waitcnt lgkmcnt(0)
	v_add_f32_e32 v182, v182, v185
	v_mov_b32_e32 v184, 0x358637bd
	v_fmamk_f32 v180, v180, 0x3a800000, v184
	v_fmamk_f32 v182, v182, 0x3a800000, v184
	v_rsq_f32_e32 v186, v180
	v_rsq_f32_e32 v188, v182
	v_pk_mul_f32 v[32:33], v[32:33], v[186:187] op_sel_hi:[1,0]
	v_pk_mul_f32 v[34:35], v[34:35], v[186:187] op_sel_hi:[1,0]
	v_pk_mul_f32 v[36:37], v[36:37], v[186:187] op_sel_hi:[1,0]
	v_pk_mul_f32 v[38:39], v[38:39], v[186:187] op_sel_hi:[1,0]
	v_pk_mul_f32 v[40:41], v[40:41], v[186:187] op_sel_hi:[1,0]
	v_pk_mul_f32 v[42:43], v[42:43], v[186:187] op_sel_hi:[1,0]
	v_pk_mul_f32 v[44:45], v[44:45], v[186:187] op_sel_hi:[1,0]
	v_pk_mul_f32 v[46:47], v[46:47], v[186:187] op_sel_hi:[1,0]
	v_pk_mul_f32 v[48:49], v[48:49], v[188:189] op_sel_hi:[1,0]
	v_pk_mul_f32 v[50:51], v[50:51], v[188:189] op_sel_hi:[1,0]
	v_pk_mul_f32 v[52:53], v[52:53], v[188:189] op_sel_hi:[1,0]
	v_pk_mul_f32 v[54:55], v[54:55], v[188:189] op_sel_hi:[1,0]
	v_pk_mul_f32 v[56:57], v[56:57], v[188:189] op_sel_hi:[1,0]
	v_pk_mul_f32 v[58:59], v[58:59], v[188:189] op_sel_hi:[1,0]
	v_pk_mul_f32 v[60:61], v[60:61], v[188:189] op_sel_hi:[1,0]
	v_pk_mul_f32 v[62:63], v[62:63], v[188:189] op_sel_hi:[1,0]
	v_pk_fma_f32 v[32:33], v[32:33], v[0:1], v[16:17]
	v_pk_fma_f32 v[34:35], v[34:35], v[2:3], v[18:19]
	v_pk_fma_f32 v[36:37], v[36:37], v[4:5], v[20:21]
	v_pk_fma_f32 v[38:39], v[38:39], v[6:7], v[22:23]
	v_pk_fma_f32 v[40:41], v[40:41], v[8:9], v[24:25]
	v_pk_fma_f32 v[42:43], v[42:43], v[10:11], v[26:27]
	v_pk_fma_f32 v[44:45], v[44:45], v[12:13], v[28:29]
	v_pk_fma_f32 v[46:47], v[46:47], v[14:15], v[30:31]
	v_pk_fma_f32 v[48:49], v[48:49], v[0:1], v[16:17]
	v_pk_fma_f32 v[50:51], v[50:51], v[2:3], v[18:19]
	v_pk_fma_f32 v[52:53], v[52:53], v[4:5], v[20:21]
	v_pk_fma_f32 v[54:55], v[54:55], v[6:7], v[22:23]
	v_pk_fma_f32 v[56:57], v[56:57], v[8:9], v[24:25]
	v_pk_fma_f32 v[58:59], v[58:59], v[10:11], v[26:27]
	v_pk_fma_f32 v[60:61], v[60:61], v[12:13], v[28:29]
	v_pk_fma_f32 v[62:63], v[62:63], v[14:15], v[30:31]
	v_cvt_pk_bf16_f32 v144, v32, v33
	v_cvt_pk_bf16_f32 v145, v34, v35
	v_cvt_pk_bf16_f32 v146, v36, v37
	v_cvt_pk_bf16_f32 v147, v38, v39
	v_cvt_pk_bf16_f32 v148, v40, v41
	v_cvt_pk_bf16_f32 v149, v42, v43
	v_cvt_pk_bf16_f32 v150, v44, v45
	v_cvt_pk_bf16_f32 v151, v46, v47
	v_cvt_pk_bf16_f32 v164, v48, v49
	v_cvt_pk_bf16_f32 v165, v50, v51
	v_cvt_pk_bf16_f32 v166, v52, v53
	v_cvt_pk_bf16_f32 v167, v54, v55
	v_cvt_pk_bf16_f32 v168, v56, v57
	v_cvt_pk_bf16_f32 v169, v58, v59
	v_cvt_pk_bf16_f32 v170, v60, v61
	v_cvt_pk_bf16_f32 v171, v62, v63
	global_store_dwordx4 v179, v[144:147], s[18:19] offset:-2048
	global_store_dwordx4 v179, v[148:151], s[18:19] offset:-1024
	global_store_dwordx4 v179, v[164:167], s[18:19] offset:0
	global_store_dwordx4 v179, v[168:171], s[18:19] offset:1024
	s_add_u32 s10, s10, s14
	s_cmp_lt_u32 s10, 0x200
	s_cbranch_scc1 .Lp1_cpair
